# P9: rolling half-token gather pipeline (rows 0-15 / 16-31 register sets refilled with the next token's rows as soon as consumed, 32 gathers always in flight)
# baseline (speedup 1.0000x reference)
; DI void wave_lds_sync() { asm volatile("s_waitcnt lgkmcnt(0)" ::: "memory"); __builtin_amdgcn_wave_barrier(); }
; DI void phase9(const Params& p, char* smem, int rep) {
;     ...
;   xcd_queue((unsigned*)(p.ws + WS_BAR) + CTR_UQ + rep * 8, 512, smem, [&](int s, int c) __attribute__((always_inline)) {
; #pragma unroll 1
;     for (int t = 0; t < 4; ++t) {
;       const int tok = __builtin_amdgcn_readfirstlane(c * 16 + w * 4 + t);
;       const int i0 = IDS[(size_t)tok * 128 + lane], i1 = IDS[(size_t)tok * 128 + 64 + lane];
;       const u32x4 hq = *(const u32x4*)(H2Q + (size_t)tok * D_ + s * 256 + l15 * 16);
;       wave_lds_sync();
;       lw[(lane & 3) * 32 + (lane >> 2)] = i0;
;       lw[(lane & 3) * 32 + 16 + (lane >> 2)] = i1;
;       wave_lds_sync();
;       const unsigned char* ub = U8 + s * 256 + l15 * 16;
; #pragma unroll
;       for (int batch = 0; batch < 2; ++batch) {
;         int ida[16];
; #pragma unroll
;         for (int q = 0; q < 4; ++q) { const int4 v = *(const int4*)(lw + g * 32 + batch * 16 + q * 4); ida[q * 4] = v.x; ida[q * 4 + 1] = v.y; ida[q * 4 + 2] = v.z; ida[q * 4 + 3] = v.w; }
;         u32x4 rows[16];
; #pragma unroll
;         for (int k = 0; k < 16; ++k) rows[k] = *(const u32x4*)(ub + (size_t)ida[k] * 2048);
;         int part[16];
; #pragma unroll
;         for (int k = 0; k < 16; ++k) {
;           int acc = 0;
; #pragma unroll
;           for (int d = 0; d < 4; ++d) acc = __builtin_amdgcn_sdot4((int)rows[k][d], (int)hq[d], acc, false);
.Lp9_fill:
	s_waitcnt vmcnt(0)
	s_lshl_b32 s47, s34, 9
	s_add_u32 s42, s6, s47
	s_addc_u32 s43, s7, 0
	global_load_dword v10, v3, s[42:43]
	global_load_dword v11, v3, s[42:43] offset:256
	s_waitcnt vmcnt(0)
	ds_write2_b32 v5, v10, v11 offset0:4 offset1:20
	s_waitcnt lgkmcnt(0)
	ds_read_b128 v[20:23], v6 offset:16
	ds_read_b128 v[24:27], v6 offset:32
	ds_read_b128 v[28:31], v6 offset:48
	ds_read_b128 v[32:35], v6 offset:64
	ds_read_b128 v[36:39], v6 offset:80
	ds_read_b128 v[40:43], v6 offset:96
	ds_read_b128 v[44:47], v6 offset:112
	ds_read_b128 v[48:51], v6 offset:128
	s_add_i32 s37, s34, 1
	s_lshl_b32 s47, s37, 9
	s_add_u32 s42, s6, s47
	s_addc_u32 s43, s7, 0
	global_load_dword v10, v3, s[42:43]
	global_load_dword v11, v3, s[42:43] offset:256
	s_lshl_b32 s47, s34, 11
	s_add_u32 s44, s22, s47
	s_addc_u32 s45, s23, 0
	global_load_dwordx4 v[12:15], v2, s[44:45]
	s_waitcnt lgkmcnt(0)
	v_lshl_add_u32 v20, v20, 11, v2
	v_lshl_add_u32 v21, v21, 11, v2
	v_lshl_add_u32 v22, v22, 11, v2
	v_lshl_add_u32 v23, v23, 11, v2
	v_lshl_add_u32 v24, v24, 11, v2
	v_lshl_add_u32 v25, v25, 11, v2
	v_lshl_add_u32 v26, v26, 11, v2
	v_lshl_add_u32 v27, v27, 11, v2
	v_lshl_add_u32 v28, v28, 11, v2
	v_lshl_add_u32 v29, v29, 11, v2
	v_lshl_add_u32 v30, v30, 11, v2
	v_lshl_add_u32 v31, v31, 11, v2
	v_lshl_add_u32 v32, v32, 11, v2
	v_lshl_add_u32 v33, v33, 11, v2
	v_lshl_add_u32 v34, v34, 11, v2
	v_lshl_add_u32 v35, v35, 11, v2
	global_load_dwordx4 v[84:87], v20, s[20:21]
	global_load_dwordx4 v[88:91], v21, s[20:21]
	global_load_dwordx4 v[92:95], v22, s[20:21]
	global_load_dwordx4 v[96:99], v23, s[20:21]
	global_load_dwordx4 v[100:103], v24, s[20:21]
	global_load_dwordx4 v[104:107], v25, s[20:21]
	global_load_dwordx4 v[108:111], v26, s[20:21]
	global_load_dwordx4 v[112:115], v27, s[20:21]
	global_load_dwordx4 v[116:119], v28, s[20:21]
	global_load_dwordx4 v[120:123], v29, s[20:21]
	global_load_dwordx4 v[124:127], v30, s[20:21]
	global_load_dwordx4 v[128:131], v31, s[20:21]
	global_load_dwordx4 v[132:135], v32, s[20:21]
	global_load_dwordx4 v[136:139], v33, s[20:21]
	global_load_dwordx4 v[140:143], v34, s[20:21]
	global_load_dwordx4 v[144:147], v35, s[20:21]
	global_load_dword v245, v3, s[42:43]
	v_lshl_add_u32 v36, v36, 11, v2
	v_lshl_add_u32 v37, v37, 11, v2
	v_lshl_add_u32 v38, v38, 11, v2
	v_lshl_add_u32 v39, v39, 11, v2
	v_lshl_add_u32 v40, v40, 11, v2
	v_lshl_add_u32 v41, v41, 11, v2
	v_lshl_add_u32 v42, v42, 11, v2
	v_lshl_add_u32 v43, v43, 11, v2
	v_lshl_add_u32 v44, v44, 11, v2
	v_lshl_add_u32 v45, v45, 11, v2
	v_lshl_add_u32 v46, v46, 11, v2
	v_lshl_add_u32 v47, v47, 11, v2
	v_lshl_add_u32 v48, v48, 11, v2
	v_lshl_add_u32 v49, v49, 11, v2
	v_lshl_add_u32 v50, v50, 11, v2
	v_lshl_add_u32 v51, v51, 11, v2
	global_load_dwordx4 v[148:151], v36, s[20:21]
	global_load_dwordx4 v[152:155], v37, s[20:21]
	global_load_dwordx4 v[156:159], v38, s[20:21]
	global_load_dwordx4 v[160:163], v39, s[20:21]
	global_load_dwordx4 v[164:167], v40, s[20:21]
	global_load_dwordx4 v[168:171], v41, s[20:21]
	global_load_dwordx4 v[172:175], v42, s[20:21]
	global_load_dwordx4 v[176:179], v43, s[20:21]
	global_load_dwordx4 v[180:183], v44, s[20:21]
	global_load_dwordx4 v[184:187], v45, s[20:21]
	global_load_dwordx4 v[190:193], v46, s[20:21]
	global_load_dwordx4 v[194:197], v47, s[20:21]
	global_load_dwordx4 v[198:201], v48, s[20:21]
	global_load_dwordx4 v[202:205], v49, s[20:21]
	global_load_dwordx4 v[206:209], v50, s[20:21]
	global_load_dwordx4 v[210:213], v51, s[20:21]
	global_load_dword v245, v3, s[42:43]
	s_mov_b32 s48, 0
.Lp9_body:
	s_add_i32 s36, s34, 0
	s_lshl_b32 s46, s36, 9
	s_add_i32 s46, s46, s24
	s_add_i32 s51, s48, 1
	s_add_i32 s56, s34, 4
	s_cmp_lt_u32 s51, s49
	s_cselect_b32 s56, s56, 8192
	s_cmp_lt_u32 s56, 8192
	s_cselect_b32 s57, 1, 0
	v_mov_b32_e32 v52, 0
	v_mov_b32_e32 v53, 0
	v_mov_b32_e32 v54, 0
	v_mov_b32_e32 v55, 0
	v_mov_b32_e32 v56, 0
	v_mov_b32_e32 v57, 0
	v_mov_b32_e32 v58, 0
	v_mov_b32_e32 v59, 0
	v_mov_b32_e32 v60, 0
	v_mov_b32_e32 v61, 0
	v_mov_b32_e32 v62, 0
	v_mov_b32_e32 v63, 0
	v_mov_b32_e32 v64, 0
	v_mov_b32_e32 v65, 0
	v_mov_b32_e32 v66, 0
	v_mov_b32_e32 v67, 0
	v_mov_b32_e32 v68, 0
	v_mov_b32_e32 v69, 0
	v_mov_b32_e32 v70, 0
	v_mov_b32_e32 v71, 0
	v_mov_b32_e32 v72, 0
	v_mov_b32_e32 v73, 0
	v_mov_b32_e32 v74, 0
	v_mov_b32_e32 v75, 0
	v_mov_b32_e32 v76, 0
	v_mov_b32_e32 v77, 0
	v_mov_b32_e32 v78, 0
	v_mov_b32_e32 v79, 0
	v_mov_b32_e32 v80, 0
	v_mov_b32_e32 v81, 0
	v_mov_b32_e32 v82, 0
	v_mov_b32_e32 v83, 0
	s_waitcnt vmcnt(33)
	v_dot4c_i32_i8_e32 v52, v84, v12
	s_waitcnt vmcnt(32)
	v_dot4c_i32_i8_e32 v53, v88, v12
	s_waitcnt vmcnt(31)
	v_dot4c_i32_i8_e32 v54, v92, v12
	s_waitcnt vmcnt(30)
	v_dot4c_i32_i8_e32 v55, v96, v12
	s_waitcnt vmcnt(29)
	v_dot4c_i32_i8_e32 v56, v100, v12
	s_waitcnt vmcnt(28)
	v_dot4c_i32_i8_e32 v57, v104, v12
	s_waitcnt vmcnt(27)
	v_dot4c_i32_i8_e32 v58, v108, v12
	s_waitcnt vmcnt(26)
	v_dot4c_i32_i8_e32 v59, v112, v12
	s_waitcnt vmcnt(25)
	v_dot4c_i32_i8_e32 v60, v116, v12
	s_waitcnt vmcnt(24)
	v_dot4c_i32_i8_e32 v61, v120, v12
	s_waitcnt vmcnt(23)
	v_dot4c_i32_i8_e32 v62, v124, v12
	s_waitcnt vmcnt(22)
	v_dot4c_i32_i8_e32 v63, v128, v12
	s_waitcnt vmcnt(21)
	v_dot4c_i32_i8_e32 v64, v132, v12
	s_waitcnt vmcnt(20)
	v_dot4c_i32_i8_e32 v65, v136, v12
	s_waitcnt vmcnt(19)
	v_dot4c_i32_i8_e32 v66, v140, v12
	s_waitcnt vmcnt(18)
; DI void phase9(const Params& p, char* smem, int rep) {
;     ...
;         for (int k = 0; k < 16; ++k) rows[k] = *(const u32x4*)(ub + (size_t)ida[k] * 2048);
;         int part[16];
; #pragma unroll
;         for (int k = 0; k < 16; ++k) {
;           int acc = 0;
; #pragma unroll
;           for (int d = 0; d < 4; ++d) acc = __builtin_amdgcn_sdot4((int)rows[k][d], (int)hq[d], acc, false);
;           part[k] = acc;
;         }
;         int q8[8], q4[4], q2[2];
; #pragma unroll
;         for (int k = 0; k < 8; ++k) q8[k] = (b3 ? part[8 + k] : part[k]) + __shfl_xor(b3 ? part[k] : part[8 + k], 8);
; #pragma unroll
;         for (int k = 0; k < 4; ++k) q4[k] = (b2 ? q8[4 + k] : q8[k]) + __shfl_xor(b2 ? q8[k] : q8[4 + k], 4);
; #pragma unroll
;         for (int k = 0; k < 2; ++k) q2[k] = (b1 ? q4[2 + k] : q4[k]) + __shfl_xor(b1 ? q4[k] : q4[2 + k], 2);
;         const int rr = (b0 ? q2[1] : q2[0]) + __shfl_xor(b0 ? q2[0] : q2[1], 1);
;         PA[((size_t)s * T_ + tok) * 128 + 4 * (batch * 16 + l15) + g] = rr;
	v_dot4c_i32_i8_e32 v67, v144, v12
	v_dot4c_i32_i8_e32 v52, v85, v13
	v_dot4c_i32_i8_e32 v53, v89, v13
	v_dot4c_i32_i8_e32 v54, v93, v13
	v_dot4c_i32_i8_e32 v55, v97, v13
	v_dot4c_i32_i8_e32 v56, v101, v13
	v_dot4c_i32_i8_e32 v57, v105, v13
	v_dot4c_i32_i8_e32 v58, v109, v13
	v_dot4c_i32_i8_e32 v59, v113, v13
	v_dot4c_i32_i8_e32 v60, v117, v13
	v_dot4c_i32_i8_e32 v61, v121, v13
	v_dot4c_i32_i8_e32 v62, v125, v13
	v_dot4c_i32_i8_e32 v63, v129, v13
	v_dot4c_i32_i8_e32 v64, v133, v13
	v_dot4c_i32_i8_e32 v65, v137, v13
	v_dot4c_i32_i8_e32 v66, v141, v13
	v_dot4c_i32_i8_e32 v67, v145, v13
	v_dot4c_i32_i8_e32 v52, v86, v14
	v_dot4c_i32_i8_e32 v53, v90, v14
	v_dot4c_i32_i8_e32 v54, v94, v14
	v_dot4c_i32_i8_e32 v55, v98, v14
	v_dot4c_i32_i8_e32 v56, v102, v14
	v_dot4c_i32_i8_e32 v57, v106, v14
	v_dot4c_i32_i8_e32 v58, v110, v14
	v_dot4c_i32_i8_e32 v59, v114, v14
	v_dot4c_i32_i8_e32 v60, v118, v14
	v_dot4c_i32_i8_e32 v61, v122, v14
	v_dot4c_i32_i8_e32 v62, v126, v14
	v_dot4c_i32_i8_e32 v63, v130, v14
	v_dot4c_i32_i8_e32 v64, v134, v14
	v_dot4c_i32_i8_e32 v65, v138, v14
	v_dot4c_i32_i8_e32 v66, v142, v14
	v_dot4c_i32_i8_e32 v67, v146, v14
	v_dot4c_i32_i8_e32 v52, v87, v15
	v_dot4c_i32_i8_e32 v53, v91, v15
	v_dot4c_i32_i8_e32 v54, v95, v15
	v_dot4c_i32_i8_e32 v55, v99, v15
	v_dot4c_i32_i8_e32 v56, v103, v15
	v_dot4c_i32_i8_e32 v57, v107, v15
	v_dot4c_i32_i8_e32 v58, v111, v15
	v_dot4c_i32_i8_e32 v59, v115, v15
	v_dot4c_i32_i8_e32 v60, v119, v15
	v_dot4c_i32_i8_e32 v61, v123, v15
	v_dot4c_i32_i8_e32 v62, v127, v15
	v_dot4c_i32_i8_e32 v63, v131, v15
	v_dot4c_i32_i8_e32 v64, v135, v15
	v_dot4c_i32_i8_e32 v65, v139, v15
	v_dot4c_i32_i8_e32 v66, v143, v15
	v_dot4c_i32_i8_e32 v67, v147, v15
	ds_write2_b32 v5, v10, v11 offset0:4 offset1:20
	s_waitcnt lgkmcnt(0)
	ds_read_b128 v[20:23], v6 offset:16
	ds_read_b128 v[24:27], v6 offset:32
	ds_read_b128 v[28:31], v6 offset:48
	ds_read_b128 v[32:35], v6 offset:64
	ds_read_b128 v[36:39], v6 offset:80
	ds_read_b128 v[40:43], v6 offset:96
	ds_read_b128 v[44:47], v6 offset:112
	ds_read_b128 v[48:51], v6 offset:128
	s_add_i32 s37, s34, 2
	s_lshl_b32 s47, s37, 9
	s_add_u32 s42, s6, s47
	s_addc_u32 s43, s7, 0
	global_load_dword v10, v3, s[42:43]
	global_load_dword v11, v3, s[42:43] offset:256
	s_add_i32 s37, s34, 1
	s_lshl_b32 s47, s37, 11
	s_add_u32 s44, s22, s47
	s_addc_u32 s45, s23, 0
	global_load_dwordx4 v[16:19], v2, s[44:45]
	s_waitcnt lgkmcnt(0)
	v_lshl_add_u32 v20, v20, 11, v2
	v_lshl_add_u32 v21, v21, 11, v2
	v_lshl_add_u32 v22, v22, 11, v2
	v_lshl_add_u32 v23, v23, 11, v2
	v_lshl_add_u32 v24, v24, 11, v2
	v_lshl_add_u32 v25, v25, 11, v2
	v_lshl_add_u32 v26, v26, 11, v2
	v_lshl_add_u32 v27, v27, 11, v2
	v_lshl_add_u32 v28, v28, 11, v2
	v_lshl_add_u32 v29, v29, 11, v2
	v_lshl_add_u32 v30, v30, 11, v2
	v_lshl_add_u32 v31, v31, 11, v2
	v_lshl_add_u32 v32, v32, 11, v2
	v_lshl_add_u32 v33, v33, 11, v2
	v_lshl_add_u32 v34, v34, 11, v2
	v_lshl_add_u32 v35, v35, 11, v2
	global_load_dwordx4 v[84:87], v20, s[20:21]
	global_load_dwordx4 v[88:91], v21, s[20:21]
	global_load_dwordx4 v[92:95], v22, s[20:21]
	global_load_dwordx4 v[96:99], v23, s[20:21]
	global_load_dwordx4 v[100:103], v24, s[20:21]
	global_load_dwordx4 v[104:107], v25, s[20:21]
	global_load_dwordx4 v[108:111], v26, s[20:21]
	global_load_dwordx4 v[112:115], v27, s[20:21]
	global_load_dwordx4 v[116:119], v28, s[20:21]
	global_load_dwordx4 v[120:123], v29, s[20:21]
	global_load_dwordx4 v[124:127], v30, s[20:21]
	global_load_dwordx4 v[128:131], v31, s[20:21]
	global_load_dwordx4 v[132:135], v32, s[20:21]
	global_load_dwordx4 v[136:139], v33, s[20:21]
	global_load_dwordx4 v[140:143], v34, s[20:21]
	global_load_dwordx4 v[144:147], v35, s[20:21]
	v_add_u32_dpp v221, v52, v52 row_ror:8 row_mask:0xf bank_mask:0x3
	v_add_u32_dpp v221, v60, v60 row_ror:8 row_mask:0xf bank_mask:0xc
	v_add_u32_dpp v222, v53, v53 row_ror:8 row_mask:0xf bank_mask:0x3
	v_add_u32_dpp v222, v61, v61 row_ror:8 row_mask:0xf bank_mask:0xc
	v_add_u32_dpp v223, v54, v54 row_ror:8 row_mask:0xf bank_mask:0x3
	v_add_u32_dpp v223, v62, v62 row_ror:8 row_mask:0xf bank_mask:0xc
	v_add_u32_dpp v224, v55, v55 row_ror:8 row_mask:0xf bank_mask:0x3
	v_add_u32_dpp v224, v63, v63 row_ror:8 row_mask:0xf bank_mask:0xc
	v_add_u32_dpp v225, v56, v56 row_ror:8 row_mask:0xf bank_mask:0x3
	v_add_u32_dpp v225, v64, v64 row_ror:8 row_mask:0xf bank_mask:0xc
	v_add_u32_dpp v226, v57, v57 row_ror:8 row_mask:0xf bank_mask:0x3
	v_add_u32_dpp v226, v65, v65 row_ror:8 row_mask:0xf bank_mask:0xc
	v_add_u32_dpp v227, v58, v58 row_ror:8 row_mask:0xf bank_mask:0x3
	v_add_u32_dpp v227, v66, v66 row_ror:8 row_mask:0xf bank_mask:0xc
	v_add_u32_dpp v228, v59, v59 row_ror:8 row_mask:0xf bank_mask:0x3
	v_add_u32_dpp v228, v67, v67 row_ror:8 row_mask:0xf bank_mask:0xc
	v_add_u32_dpp v229, v221, v221 row_half_mirror row_mask:0xf bank_mask:0x5
	v_add_u32_dpp v229, v225, v225 row_half_mirror row_mask:0xf bank_mask:0xa
	v_add_u32_dpp v230, v222, v222 row_half_mirror row_mask:0xf bank_mask:0x5
	v_add_u32_dpp v230, v226, v226 row_half_mirror row_mask:0xf bank_mask:0xa
	v_add_u32_dpp v231, v223, v223 row_half_mirror row_mask:0xf bank_mask:0x5
	v_add_u32_dpp v231, v227, v227 row_half_mirror row_mask:0xf bank_mask:0xa
	v_add_u32_dpp v232, v224, v224 row_half_mirror row_mask:0xf bank_mask:0x5
	v_add_u32_dpp v232, v228, v228 row_half_mirror row_mask:0xf bank_mask:0xa
	v_add_u32_dpp v233, v229, v229 quad_perm:[2,3,0,1] row_mask:0xf bank_mask:0xf
	v_add_u32_dpp v234, v230, v230 quad_perm:[2,3,0,1] row_mask:0xf bank_mask:0xf
	v_add_u32_dpp v235, v231, v231 quad_perm:[2,3,0,1] row_mask:0xf bank_mask:0xf
	s_nop 0
	v_add_u32_dpp v236, v232, v232 quad_perm:[2,3,0,1] row_mask:0xf bank_mask:0xf
	v_cndmask_b32_e64 v237, v235, v233, s[2:3]
	v_cndmask_b32_e64 v238, v236, v234, s[2:3]
	v_add_u32_e32 v214, s46, v4
	s_nop 1
	v_add_u32_dpp v239, v237, v237 quad_perm:[1,0,3,2] row_mask:0xf bank_mask:0xf
	v_add_u32_dpp v240, v238, v238 quad_perm:[1,0,3,2] row_mask:0xf bank_mask:0xf
	v_cndmask_b32_e64 v241, v240, v239, s[4:5]
	global_store_dword v214, v241, s[14:15]
	s_waitcnt vmcnt(36)
; DI void phase9(const Params& p, char* smem, int rep) {
;     ...
;         for (int k = 0; k < 16; ++k) rows[k] = *(const u32x4*)(ub + (size_t)ida[k] * 2048);
;         int part[16];
; #pragma unroll
;         for (int k = 0; k < 16; ++k) {
;           int acc = 0;
; #pragma unroll
;           for (int d = 0; d < 4; ++d) acc = __builtin_amdgcn_sdot4((int)rows[k][d], (int)hq[d], acc, false);
;           part[k] = acc;
;         }
;         int q8[8], q4[4], q2[2];
; #pragma unroll
;         for (int k = 0; k < 8; ++k) q8[k] = (b3 ? part[8 + k] : part[k]) + __shfl_xor(b3 ? part[k] : part[8 + k], 8);
; #pragma unroll
;         for (int k = 0; k < 4; ++k) q4[k] = (b2 ? q8[4 + k] : q8[k]) + __shfl_xor(b2 ? q8[k] : q8[4 + k], 4);
; #pragma unroll
;         for (int k = 0; k < 2; ++k) q2[k] = (b1 ? q4[2 + k] : q4[k]) + __shfl_xor(b1 ? q4[k] : q4[2 + k], 2);
;         const int rr = (b0 ? q2[1] : q2[0]) + __shfl_xor(b0 ? q2[0] : q2[1], 1);
;         PA[((size_t)s * T_ + tok) * 128 + 4 * (batch * 16 + l15) + g] = rr;
	v_dot4c_i32_i8_e32 v68, v148, v12
	s_waitcnt vmcnt(35)
	v_dot4c_i32_i8_e32 v69, v152, v12
	s_waitcnt vmcnt(34)
	v_dot4c_i32_i8_e32 v70, v156, v12
	s_waitcnt vmcnt(33)
	v_dot4c_i32_i8_e32 v71, v160, v12
	s_waitcnt vmcnt(32)
	v_dot4c_i32_i8_e32 v72, v164, v12
	s_waitcnt vmcnt(31)
	v_dot4c_i32_i8_e32 v73, v168, v12
	s_waitcnt vmcnt(30)
	v_dot4c_i32_i8_e32 v74, v172, v12
	s_waitcnt vmcnt(29)
	v_dot4c_i32_i8_e32 v75, v176, v12
	s_waitcnt vmcnt(28)
	v_dot4c_i32_i8_e32 v76, v180, v12
	s_waitcnt vmcnt(27)
	v_dot4c_i32_i8_e32 v77, v184, v12
	s_waitcnt vmcnt(26)
	v_dot4c_i32_i8_e32 v78, v190, v12
	s_waitcnt vmcnt(25)
	v_dot4c_i32_i8_e32 v79, v194, v12
	s_waitcnt vmcnt(24)
	v_dot4c_i32_i8_e32 v80, v198, v12
	s_waitcnt vmcnt(23)
	v_dot4c_i32_i8_e32 v81, v202, v12
	s_waitcnt vmcnt(22)
	v_dot4c_i32_i8_e32 v82, v206, v12
	s_waitcnt vmcnt(21)
	v_dot4c_i32_i8_e32 v83, v210, v12
	v_dot4c_i32_i8_e32 v68, v149, v13
	v_dot4c_i32_i8_e32 v69, v153, v13
	v_dot4c_i32_i8_e32 v70, v157, v13
	v_dot4c_i32_i8_e32 v71, v161, v13
	v_dot4c_i32_i8_e32 v72, v165, v13
	v_dot4c_i32_i8_e32 v73, v169, v13
	v_dot4c_i32_i8_e32 v74, v173, v13
	v_dot4c_i32_i8_e32 v75, v177, v13
	v_dot4c_i32_i8_e32 v76, v181, v13
	v_dot4c_i32_i8_e32 v77, v185, v13
	v_dot4c_i32_i8_e32 v78, v191, v13
	v_dot4c_i32_i8_e32 v79, v195, v13
	v_dot4c_i32_i8_e32 v80, v199, v13
	v_dot4c_i32_i8_e32 v81, v203, v13
	v_dot4c_i32_i8_e32 v82, v207, v13
	v_dot4c_i32_i8_e32 v83, v211, v13
	v_dot4c_i32_i8_e32 v68, v150, v14
	v_dot4c_i32_i8_e32 v69, v154, v14
	v_dot4c_i32_i8_e32 v70, v158, v14
	v_dot4c_i32_i8_e32 v71, v162, v14
	v_dot4c_i32_i8_e32 v72, v166, v14
	v_dot4c_i32_i8_e32 v73, v170, v14
	v_dot4c_i32_i8_e32 v74, v174, v14
	v_dot4c_i32_i8_e32 v75, v178, v14
	v_dot4c_i32_i8_e32 v76, v182, v14
	v_dot4c_i32_i8_e32 v77, v186, v14
	v_dot4c_i32_i8_e32 v78, v192, v14
	v_dot4c_i32_i8_e32 v79, v196, v14
	v_dot4c_i32_i8_e32 v80, v200, v14
	v_dot4c_i32_i8_e32 v81, v204, v14
	v_dot4c_i32_i8_e32 v82, v208, v14
	v_dot4c_i32_i8_e32 v83, v212, v14
	v_dot4c_i32_i8_e32 v68, v151, v15
	v_dot4c_i32_i8_e32 v69, v155, v15
	v_dot4c_i32_i8_e32 v70, v159, v15
	v_dot4c_i32_i8_e32 v71, v163, v15
	v_dot4c_i32_i8_e32 v72, v167, v15
	v_dot4c_i32_i8_e32 v73, v171, v15
	v_dot4c_i32_i8_e32 v74, v175, v15
	v_dot4c_i32_i8_e32 v75, v179, v15
	v_dot4c_i32_i8_e32 v76, v183, v15
	v_dot4c_i32_i8_e32 v77, v187, v15
	v_dot4c_i32_i8_e32 v78, v193, v15
	v_dot4c_i32_i8_e32 v79, v197, v15
	v_dot4c_i32_i8_e32 v80, v201, v15
	v_dot4c_i32_i8_e32 v81, v205, v15
	v_dot4c_i32_i8_e32 v82, v209, v15
	v_dot4c_i32_i8_e32 v83, v213, v15
	v_lshl_add_u32 v36, v36, 11, v2
	v_lshl_add_u32 v37, v37, 11, v2
	v_lshl_add_u32 v38, v38, 11, v2
	v_lshl_add_u32 v39, v39, 11, v2
	v_lshl_add_u32 v40, v40, 11, v2
	v_lshl_add_u32 v41, v41, 11, v2
	v_lshl_add_u32 v42, v42, 11, v2
	v_lshl_add_u32 v43, v43, 11, v2
	v_lshl_add_u32 v44, v44, 11, v2
	v_lshl_add_u32 v45, v45, 11, v2
	v_lshl_add_u32 v46, v46, 11, v2
	v_lshl_add_u32 v47, v47, 11, v2
	v_lshl_add_u32 v48, v48, 11, v2
	v_lshl_add_u32 v49, v49, 11, v2
	v_lshl_add_u32 v50, v50, 11, v2
	v_lshl_add_u32 v51, v51, 11, v2
	global_load_dwordx4 v[148:151], v36, s[20:21]
	global_load_dwordx4 v[152:155], v37, s[20:21]
	global_load_dwordx4 v[156:159], v38, s[20:21]
	global_load_dwordx4 v[160:163], v39, s[20:21]
	global_load_dwordx4 v[164:167], v40, s[20:21]
	global_load_dwordx4 v[168:171], v41, s[20:21]
	global_load_dwordx4 v[172:175], v42, s[20:21]
	global_load_dwordx4 v[176:179], v43, s[20:21]
	global_load_dwordx4 v[180:183], v44, s[20:21]
	global_load_dwordx4 v[184:187], v45, s[20:21]
	global_load_dwordx4 v[190:193], v46, s[20:21]
	global_load_dwordx4 v[194:197], v47, s[20:21]
	global_load_dwordx4 v[198:201], v48, s[20:21]
	global_load_dwordx4 v[202:205], v49, s[20:21]
	global_load_dwordx4 v[206:209], v50, s[20:21]
	global_load_dwordx4 v[210:213], v51, s[20:21]
	v_add_u32_dpp v221, v68, v68 row_ror:8 row_mask:0xf bank_mask:0x3
	v_add_u32_dpp v221, v76, v76 row_ror:8 row_mask:0xf bank_mask:0xc
	v_add_u32_dpp v222, v69, v69 row_ror:8 row_mask:0xf bank_mask:0x3
	v_add_u32_dpp v222, v77, v77 row_ror:8 row_mask:0xf bank_mask:0xc
	v_add_u32_dpp v223, v70, v70 row_ror:8 row_mask:0xf bank_mask:0x3
	v_add_u32_dpp v223, v78, v78 row_ror:8 row_mask:0xf bank_mask:0xc
	v_add_u32_dpp v224, v71, v71 row_ror:8 row_mask:0xf bank_mask:0x3
	v_add_u32_dpp v224, v79, v79 row_ror:8 row_mask:0xf bank_mask:0xc
	v_add_u32_dpp v225, v72, v72 row_ror:8 row_mask:0xf bank_mask:0x3
	v_add_u32_dpp v225, v80, v80 row_ror:8 row_mask:0xf bank_mask:0xc
	v_add_u32_dpp v226, v73, v73 row_ror:8 row_mask:0xf bank_mask:0x3
	v_add_u32_dpp v226, v81, v81 row_ror:8 row_mask:0xf bank_mask:0xc
	v_add_u32_dpp v227, v74, v74 row_ror:8 row_mask:0xf bank_mask:0x3
	v_add_u32_dpp v227, v82, v82 row_ror:8 row_mask:0xf bank_mask:0xc
	v_add_u32_dpp v228, v75, v75 row_ror:8 row_mask:0xf bank_mask:0x3
	v_add_u32_dpp v228, v83, v83 row_ror:8 row_mask:0xf bank_mask:0xc
	v_add_u32_dpp v229, v221, v221 row_half_mirror row_mask:0xf bank_mask:0x5
	v_add_u32_dpp v229, v225, v225 row_half_mirror row_mask:0xf bank_mask:0xa
	v_add_u32_dpp v230, v222, v222 row_half_mirror row_mask:0xf bank_mask:0x5
	v_add_u32_dpp v230, v226, v226 row_half_mirror row_mask:0xf bank_mask:0xa
	v_add_u32_dpp v231, v223, v223 row_half_mirror row_mask:0xf bank_mask:0x5
	v_add_u32_dpp v231, v227, v227 row_half_mirror row_mask:0xf bank_mask:0xa
	v_add_u32_dpp v232, v224, v224 row_half_mirror row_mask:0xf bank_mask:0x5
	v_add_u32_dpp v232, v228, v228 row_half_mirror row_mask:0xf bank_mask:0xa
	v_add_u32_dpp v233, v229, v229 quad_perm:[2,3,0,1] row_mask:0xf bank_mask:0xf
	v_add_u32_dpp v234, v230, v230 quad_perm:[2,3,0,1] row_mask:0xf bank_mask:0xf
; DI void wave_lds_sync() { asm volatile("s_waitcnt lgkmcnt(0)" ::: "memory"); __builtin_amdgcn_wave_barrier(); }
; DI void phase9(const Params& p, char* smem, int rep) {
;     ...
;       const int tok = __builtin_amdgcn_readfirstlane(c * 16 + w * 4 + t);
;       const int i0 = IDS[(size_t)tok * 128 + lane], i1 = IDS[(size_t)tok * 128 + 64 + lane];
;       const u32x4 hq = *(const u32x4*)(H2Q + (size_t)tok * D_ + s * 256 + l15 * 16);
;       wave_lds_sync();
;       lw[(lane & 3) * 32 + (lane >> 2)] = i0;
;       lw[(lane & 3) * 32 + 16 + (lane >> 2)] = i1;
;       wave_lds_sync();
;       const unsigned char* ub = U8 + s * 256 + l15 * 16;
; #pragma unroll
;       for (int batch = 0; batch < 2; ++batch) {
;         int ida[16];
; #pragma unroll
;         for (int q = 0; q < 4; ++q) { const int4 v = *(const int4*)(lw + g * 32 + batch * 16 + q * 4); ida[q * 4] = v.x; ida[q * 4 + 1] = v.y; ida[q * 4 + 2] = v.z; ida[q * 4 + 3] = v.w; }
;         u32x4 rows[16];
; #pragma unroll
;         for (int k = 0; k < 16; ++k) rows[k] = *(const u32x4*)(ub + (size_t)ida[k] * 2048);
;         int part[16];
; #pragma unroll
;         for (int k = 0; k < 16; ++k) {
;           int acc = 0;
; #pragma unroll
;           for (int d = 0; d < 4; ++d) acc = __builtin_amdgcn_sdot4((int)rows[k][d], (int)hq[d], acc, false);
;     ...
;         for (int k = 0; k < 8; ++k) q8[k] = (b3 ? part[8 + k] : part[k]) + __shfl_xor(b3 ? part[k] : part[8 + k], 8);
; #pragma unroll
;         for (int k = 0; k < 4; ++k) q4[k] = (b2 ? q8[4 + k] : q8[k]) + __shfl_xor(b2 ? q8[k] : q8[4 + k], 4);
; #pragma unroll
;         for (int k = 0; k < 2; ++k) q2[k] = (b1 ? q4[2 + k] : q4[k]) + __shfl_xor(b1 ? q4[k] : q4[2 + k], 2);
;         const int rr = (b0 ? q2[1] : q2[0]) + __shfl_xor(b0 ? q2[0] : q2[1], 1);
;         PA[((size_t)s * T_ + tok) * 128 + 4 * (batch * 16 + l15) + g] = rr;
	v_add_u32_dpp v235, v231, v231 quad_perm:[2,3,0,1] row_mask:0xf bank_mask:0xf
	s_nop 0
	v_add_u32_dpp v236, v232, v232 quad_perm:[2,3,0,1] row_mask:0xf bank_mask:0xf
	v_cndmask_b32_e64 v237, v235, v233, s[2:3]
	v_cndmask_b32_e64 v238, v236, v234, s[2:3]
	s_nop 0
	s_nop 1
	v_add_u32_dpp v239, v237, v237 quad_perm:[1,0,3,2] row_mask:0xf bank_mask:0xf
	v_add_u32_dpp v240, v238, v238 quad_perm:[1,0,3,2] row_mask:0xf bank_mask:0xf
	v_cndmask_b32_e64 v241, v240, v239, s[4:5]
	global_store_dword v214, v241, s[14:15] offset:256
	s_add_i32 s36, s34, 1
	s_lshl_b32 s46, s36, 9
	s_add_i32 s46, s46, s24
	s_add_i32 s51, s48, 1
	s_add_i32 s56, s34, 4
	s_cmp_lt_u32 s51, s49
	s_cselect_b32 s56, s56, 8192
	s_cmp_lt_u32 s56, 8192
	s_cselect_b32 s57, 1, 0
	v_mov_b32_e32 v52, 0
	v_mov_b32_e32 v53, 0
	v_mov_b32_e32 v54, 0
	v_mov_b32_e32 v55, 0
	v_mov_b32_e32 v56, 0
	v_mov_b32_e32 v57, 0
	v_mov_b32_e32 v58, 0
	v_mov_b32_e32 v59, 0
	v_mov_b32_e32 v60, 0
	v_mov_b32_e32 v61, 0
	v_mov_b32_e32 v62, 0
	v_mov_b32_e32 v63, 0
	v_mov_b32_e32 v64, 0
	v_mov_b32_e32 v65, 0
	v_mov_b32_e32 v66, 0
	v_mov_b32_e32 v67, 0
	v_mov_b32_e32 v68, 0
	v_mov_b32_e32 v69, 0
	v_mov_b32_e32 v70, 0
	v_mov_b32_e32 v71, 0
	v_mov_b32_e32 v72, 0
	v_mov_b32_e32 v73, 0
	v_mov_b32_e32 v74, 0
	v_mov_b32_e32 v75, 0
	v_mov_b32_e32 v76, 0
	v_mov_b32_e32 v77, 0
	v_mov_b32_e32 v78, 0
	v_mov_b32_e32 v79, 0
	v_mov_b32_e32 v80, 0
	v_mov_b32_e32 v81, 0
	v_mov_b32_e32 v82, 0
	v_mov_b32_e32 v83, 0
	s_waitcnt vmcnt(33)
	v_dot4c_i32_i8_e32 v52, v84, v16
	s_waitcnt vmcnt(32)
	v_dot4c_i32_i8_e32 v53, v88, v16
	s_waitcnt vmcnt(31)
	v_dot4c_i32_i8_e32 v54, v92, v16
	s_waitcnt vmcnt(30)
	v_dot4c_i32_i8_e32 v55, v96, v16
	s_waitcnt vmcnt(29)
	v_dot4c_i32_i8_e32 v56, v100, v16
	s_waitcnt vmcnt(28)
	v_dot4c_i32_i8_e32 v57, v104, v16
	s_waitcnt vmcnt(27)
	v_dot4c_i32_i8_e32 v58, v108, v16
	s_waitcnt vmcnt(26)
	v_dot4c_i32_i8_e32 v59, v112, v16
	s_waitcnt vmcnt(25)
	v_dot4c_i32_i8_e32 v60, v116, v16
	s_waitcnt vmcnt(24)
	v_dot4c_i32_i8_e32 v61, v120, v16
	s_waitcnt vmcnt(23)
	v_dot4c_i32_i8_e32 v62, v124, v16
	s_waitcnt vmcnt(22)
	v_dot4c_i32_i8_e32 v63, v128, v16
	s_waitcnt vmcnt(21)
	v_dot4c_i32_i8_e32 v64, v132, v16
	s_waitcnt vmcnt(20)
	v_dot4c_i32_i8_e32 v65, v136, v16
	s_waitcnt vmcnt(19)
	v_dot4c_i32_i8_e32 v66, v140, v16
	s_waitcnt vmcnt(18)
	v_dot4c_i32_i8_e32 v67, v144, v16
	v_dot4c_i32_i8_e32 v52, v85, v17
	v_dot4c_i32_i8_e32 v53, v89, v17
	v_dot4c_i32_i8_e32 v54, v93, v17
	v_dot4c_i32_i8_e32 v55, v97, v17
	v_dot4c_i32_i8_e32 v56, v101, v17
	v_dot4c_i32_i8_e32 v57, v105, v17
	v_dot4c_i32_i8_e32 v58, v109, v17
	v_dot4c_i32_i8_e32 v59, v113, v17
	v_dot4c_i32_i8_e32 v60, v117, v17
	v_dot4c_i32_i8_e32 v61, v121, v17
	v_dot4c_i32_i8_e32 v62, v125, v17
	v_dot4c_i32_i8_e32 v63, v129, v17
	v_dot4c_i32_i8_e32 v64, v133, v17
	v_dot4c_i32_i8_e32 v65, v137, v17
	v_dot4c_i32_i8_e32 v66, v141, v17
	v_dot4c_i32_i8_e32 v67, v145, v17
	v_dot4c_i32_i8_e32 v52, v86, v18
	v_dot4c_i32_i8_e32 v53, v90, v18
	v_dot4c_i32_i8_e32 v54, v94, v18
	v_dot4c_i32_i8_e32 v55, v98, v18
	v_dot4c_i32_i8_e32 v56, v102, v18
	v_dot4c_i32_i8_e32 v57, v106, v18
	v_dot4c_i32_i8_e32 v58, v110, v18
	v_dot4c_i32_i8_e32 v59, v114, v18
	v_dot4c_i32_i8_e32 v60, v118, v18
	v_dot4c_i32_i8_e32 v61, v122, v18
	v_dot4c_i32_i8_e32 v62, v126, v18
	v_dot4c_i32_i8_e32 v63, v130, v18
	v_dot4c_i32_i8_e32 v64, v134, v18
	v_dot4c_i32_i8_e32 v65, v138, v18
	v_dot4c_i32_i8_e32 v66, v142, v18
	v_dot4c_i32_i8_e32 v67, v146, v18
	v_dot4c_i32_i8_e32 v52, v87, v19
	v_dot4c_i32_i8_e32 v53, v91, v19
	v_dot4c_i32_i8_e32 v54, v95, v19
	v_dot4c_i32_i8_e32 v55, v99, v19
	v_dot4c_i32_i8_e32 v56, v103, v19
	v_dot4c_i32_i8_e32 v57, v107, v19
	v_dot4c_i32_i8_e32 v58, v111, v19
	v_dot4c_i32_i8_e32 v59, v115, v19
	v_dot4c_i32_i8_e32 v60, v119, v19
	v_dot4c_i32_i8_e32 v61, v123, v19
	v_dot4c_i32_i8_e32 v62, v127, v19
	v_dot4c_i32_i8_e32 v63, v131, v19
	v_dot4c_i32_i8_e32 v64, v135, v19
	v_dot4c_i32_i8_e32 v65, v139, v19
	v_dot4c_i32_i8_e32 v66, v143, v19
	v_dot4c_i32_i8_e32 v67, v147, v19
	ds_write2_b32 v5, v10, v11 offset0:4 offset1:20
	s_waitcnt lgkmcnt(0)
	ds_read_b128 v[20:23], v6 offset:16
	ds_read_b128 v[24:27], v6 offset:32
	ds_read_b128 v[28:31], v6 offset:48
	ds_read_b128 v[32:35], v6 offset:64
	ds_read_b128 v[36:39], v6 offset:80
	ds_read_b128 v[40:43], v6 offset:96
	ds_read_b128 v[44:47], v6 offset:112
	ds_read_b128 v[48:51], v6 offset:128
	s_add_i32 s37, s34, 3
	s_lshl_b32 s47, s37, 9
	s_add_u32 s42, s6, s47
	s_addc_u32 s43, s7, 0
	global_load_dword v10, v3, s[42:43]
	global_load_dword v11, v3, s[42:43] offset:256
	s_add_i32 s37, s34, 2
	s_lshl_b32 s47, s37, 11
	s_add_u32 s44, s22, s47
	s_addc_u32 s45, s23, 0
	global_load_dwordx4 v[12:15], v2, s[44:45]
	s_waitcnt lgkmcnt(0)
; DI void phase9(const Params& p, char* smem, int rep) {
;     ...
;         for (int q = 0; q < 4; ++q) { const int4 v = *(const int4*)(lw + g * 32 + batch * 16 + q * 4); ida[q * 4] = v.x; ida[q * 4 + 1] = v.y; ida[q * 4 + 2] = v.z; ida[q * 4 + 3] = v.w; }
;         u32x4 rows[16];
; #pragma unroll
;         for (int k = 0; k < 16; ++k) rows[k] = *(const u32x4*)(ub + (size_t)ida[k] * 2048);
;         int part[16];
; #pragma unroll
;         for (int k = 0; k < 16; ++k) {
;           int acc = 0;
; #pragma unroll
;           for (int d = 0; d < 4; ++d) acc = __builtin_amdgcn_sdot4((int)rows[k][d], (int)hq[d], acc, false);
;           part[k] = acc;
;         }
;         int q8[8], q4[4], q2[2];
; #pragma unroll
;         for (int k = 0; k < 8; ++k) q8[k] = (b3 ? part[8 + k] : part[k]) + __shfl_xor(b3 ? part[k] : part[8 + k], 8);
; #pragma unroll
;         for (int k = 0; k < 4; ++k) q4[k] = (b2 ? q8[4 + k] : q8[k]) + __shfl_xor(b2 ? q8[k] : q8[4 + k], 4);
; #pragma unroll
;         for (int k = 0; k < 2; ++k) q2[k] = (b1 ? q4[2 + k] : q4[k]) + __shfl_xor(b1 ? q4[k] : q4[2 + k], 2);
;         const int rr = (b0 ? q2[1] : q2[0]) + __shfl_xor(b0 ? q2[0] : q2[1], 1);
;         PA[((size_t)s * T_ + tok) * 128 + 4 * (batch * 16 + l15) + g] = rr;
	v_lshl_add_u32 v20, v20, 11, v2
	v_lshl_add_u32 v21, v21, 11, v2
	v_lshl_add_u32 v22, v22, 11, v2
	v_lshl_add_u32 v23, v23, 11, v2
	v_lshl_add_u32 v24, v24, 11, v2
	v_lshl_add_u32 v25, v25, 11, v2
	v_lshl_add_u32 v26, v26, 11, v2
	v_lshl_add_u32 v27, v27, 11, v2
	v_lshl_add_u32 v28, v28, 11, v2
	v_lshl_add_u32 v29, v29, 11, v2
	v_lshl_add_u32 v30, v30, 11, v2
	v_lshl_add_u32 v31, v31, 11, v2
	v_lshl_add_u32 v32, v32, 11, v2
	v_lshl_add_u32 v33, v33, 11, v2
	v_lshl_add_u32 v34, v34, 11, v2
	v_lshl_add_u32 v35, v35, 11, v2
	global_load_dwordx4 v[84:87], v20, s[20:21]
	global_load_dwordx4 v[88:91], v21, s[20:21]
	global_load_dwordx4 v[92:95], v22, s[20:21]
	global_load_dwordx4 v[96:99], v23, s[20:21]
	global_load_dwordx4 v[100:103], v24, s[20:21]
	global_load_dwordx4 v[104:107], v25, s[20:21]
	global_load_dwordx4 v[108:111], v26, s[20:21]
	global_load_dwordx4 v[112:115], v27, s[20:21]
	global_load_dwordx4 v[116:119], v28, s[20:21]
	global_load_dwordx4 v[120:123], v29, s[20:21]
	global_load_dwordx4 v[124:127], v30, s[20:21]
	global_load_dwordx4 v[128:131], v31, s[20:21]
	global_load_dwordx4 v[132:135], v32, s[20:21]
	global_load_dwordx4 v[136:139], v33, s[20:21]
	global_load_dwordx4 v[140:143], v34, s[20:21]
	global_load_dwordx4 v[144:147], v35, s[20:21]
	v_add_u32_dpp v221, v52, v52 row_ror:8 row_mask:0xf bank_mask:0x3
	v_add_u32_dpp v221, v60, v60 row_ror:8 row_mask:0xf bank_mask:0xc
	v_add_u32_dpp v222, v53, v53 row_ror:8 row_mask:0xf bank_mask:0x3
	v_add_u32_dpp v222, v61, v61 row_ror:8 row_mask:0xf bank_mask:0xc
	v_add_u32_dpp v223, v54, v54 row_ror:8 row_mask:0xf bank_mask:0x3
	v_add_u32_dpp v223, v62, v62 row_ror:8 row_mask:0xf bank_mask:0xc
	v_add_u32_dpp v224, v55, v55 row_ror:8 row_mask:0xf bank_mask:0x3
	v_add_u32_dpp v224, v63, v63 row_ror:8 row_mask:0xf bank_mask:0xc
	v_add_u32_dpp v225, v56, v56 row_ror:8 row_mask:0xf bank_mask:0x3
	v_add_u32_dpp v225, v64, v64 row_ror:8 row_mask:0xf bank_mask:0xc
	v_add_u32_dpp v226, v57, v57 row_ror:8 row_mask:0xf bank_mask:0x3
	v_add_u32_dpp v226, v65, v65 row_ror:8 row_mask:0xf bank_mask:0xc
	v_add_u32_dpp v227, v58, v58 row_ror:8 row_mask:0xf bank_mask:0x3
	v_add_u32_dpp v227, v66, v66 row_ror:8 row_mask:0xf bank_mask:0xc
	v_add_u32_dpp v228, v59, v59 row_ror:8 row_mask:0xf bank_mask:0x3
	v_add_u32_dpp v228, v67, v67 row_ror:8 row_mask:0xf bank_mask:0xc
	v_add_u32_dpp v229, v221, v221 row_half_mirror row_mask:0xf bank_mask:0x5
	v_add_u32_dpp v229, v225, v225 row_half_mirror row_mask:0xf bank_mask:0xa
	v_add_u32_dpp v230, v222, v222 row_half_mirror row_mask:0xf bank_mask:0x5
	v_add_u32_dpp v230, v226, v226 row_half_mirror row_mask:0xf bank_mask:0xa
	v_add_u32_dpp v231, v223, v223 row_half_mirror row_mask:0xf bank_mask:0x5
	v_add_u32_dpp v231, v227, v227 row_half_mirror row_mask:0xf bank_mask:0xa
	v_add_u32_dpp v232, v224, v224 row_half_mirror row_mask:0xf bank_mask:0x5
	v_add_u32_dpp v232, v228, v228 row_half_mirror row_mask:0xf bank_mask:0xa
	v_add_u32_dpp v233, v229, v229 quad_perm:[2,3,0,1] row_mask:0xf bank_mask:0xf
	v_add_u32_dpp v234, v230, v230 quad_perm:[2,3,0,1] row_mask:0xf bank_mask:0xf
	v_add_u32_dpp v235, v231, v231 quad_perm:[2,3,0,1] row_mask:0xf bank_mask:0xf
	s_nop 0
	v_add_u32_dpp v236, v232, v232 quad_perm:[2,3,0,1] row_mask:0xf bank_mask:0xf
	v_cndmask_b32_e64 v237, v235, v233, s[2:3]
	v_cndmask_b32_e64 v238, v236, v234, s[2:3]
	v_add_u32_e32 v214, s46, v4
	s_nop 1
	v_add_u32_dpp v239, v237, v237 quad_perm:[1,0,3,2] row_mask:0xf bank_mask:0xf
	v_add_u32_dpp v240, v238, v238 quad_perm:[1,0,3,2] row_mask:0xf bank_mask:0xf
	v_cndmask_b32_e64 v241, v240, v239, s[4:5]
	global_store_dword v214, v241, s[14:15]
	s_waitcnt vmcnt(36)
	v_dot4c_i32_i8_e32 v68, v148, v16
	s_waitcnt vmcnt(35)
	v_dot4c_i32_i8_e32 v69, v152, v16
	s_waitcnt vmcnt(34)
	v_dot4c_i32_i8_e32 v70, v156, v16
	s_waitcnt vmcnt(33)
	v_dot4c_i32_i8_e32 v71, v160, v16
	s_waitcnt vmcnt(32)
	v_dot4c_i32_i8_e32 v72, v164, v16
	s_waitcnt vmcnt(31)
	v_dot4c_i32_i8_e32 v73, v168, v16
	s_waitcnt vmcnt(30)
	v_dot4c_i32_i8_e32 v74, v172, v16
	s_waitcnt vmcnt(29)
	v_dot4c_i32_i8_e32 v75, v176, v16
	s_waitcnt vmcnt(28)
	v_dot4c_i32_i8_e32 v76, v180, v16
	s_waitcnt vmcnt(27)
	v_dot4c_i32_i8_e32 v77, v184, v16
	s_waitcnt vmcnt(26)
	v_dot4c_i32_i8_e32 v78, v190, v16
	s_waitcnt vmcnt(25)
	v_dot4c_i32_i8_e32 v79, v194, v16
	s_waitcnt vmcnt(24)
	v_dot4c_i32_i8_e32 v80, v198, v16
	s_waitcnt vmcnt(23)
	v_dot4c_i32_i8_e32 v81, v202, v16
	s_waitcnt vmcnt(22)
	v_dot4c_i32_i8_e32 v82, v206, v16
	s_waitcnt vmcnt(21)
; DI void phase9(const Params& p, char* smem, int rep) {
;     ...
;         for (int q = 0; q < 4; ++q) { const int4 v = *(const int4*)(lw + g * 32 + batch * 16 + q * 4); ida[q * 4] = v.x; ida[q * 4 + 1] = v.y; ida[q * 4 + 2] = v.z; ida[q * 4 + 3] = v.w; }
;         u32x4 rows[16];
; #pragma unroll
;         for (int k = 0; k < 16; ++k) rows[k] = *(const u32x4*)(ub + (size_t)ida[k] * 2048);
;         int part[16];
; #pragma unroll
;         for (int k = 0; k < 16; ++k) {
;           int acc = 0;
; #pragma unroll
;           for (int d = 0; d < 4; ++d) acc = __builtin_amdgcn_sdot4((int)rows[k][d], (int)hq[d], acc, false);
;           part[k] = acc;
;         }
;         int q8[8], q4[4], q2[2];
; #pragma unroll
;         for (int k = 0; k < 8; ++k) q8[k] = (b3 ? part[8 + k] : part[k]) + __shfl_xor(b3 ? part[k] : part[8 + k], 8);
; #pragma unroll
;         for (int k = 0; k < 4; ++k) q4[k] = (b2 ? q8[4 + k] : q8[k]) + __shfl_xor(b2 ? q8[k] : q8[4 + k], 4);
; #pragma unroll
;         for (int k = 0; k < 2; ++k) q2[k] = (b1 ? q4[2 + k] : q4[k]) + __shfl_xor(b1 ? q4[k] : q4[2 + k], 2);
;         const int rr = (b0 ? q2[1] : q2[0]) + __shfl_xor(b0 ? q2[0] : q2[1], 1);
;         PA[((size_t)s * T_ + tok) * 128 + 4 * (batch * 16 + l15) + g] = rr;
;       }
	v_dot4c_i32_i8_e32 v83, v210, v16
	v_dot4c_i32_i8_e32 v68, v149, v17
	v_dot4c_i32_i8_e32 v69, v153, v17
	v_dot4c_i32_i8_e32 v70, v157, v17
	v_dot4c_i32_i8_e32 v71, v161, v17
	v_dot4c_i32_i8_e32 v72, v165, v17
	v_dot4c_i32_i8_e32 v73, v169, v17
	v_dot4c_i32_i8_e32 v74, v173, v17
	v_dot4c_i32_i8_e32 v75, v177, v17
	v_dot4c_i32_i8_e32 v76, v181, v17
	v_dot4c_i32_i8_e32 v77, v185, v17
	v_dot4c_i32_i8_e32 v78, v191, v17
	v_dot4c_i32_i8_e32 v79, v195, v17
	v_dot4c_i32_i8_e32 v80, v199, v17
	v_dot4c_i32_i8_e32 v81, v203, v17
	v_dot4c_i32_i8_e32 v82, v207, v17
	v_dot4c_i32_i8_e32 v83, v211, v17
	v_dot4c_i32_i8_e32 v68, v150, v18
	v_dot4c_i32_i8_e32 v69, v154, v18
	v_dot4c_i32_i8_e32 v70, v158, v18
	v_dot4c_i32_i8_e32 v71, v162, v18
	v_dot4c_i32_i8_e32 v72, v166, v18
	v_dot4c_i32_i8_e32 v73, v170, v18
	v_dot4c_i32_i8_e32 v74, v174, v18
	v_dot4c_i32_i8_e32 v75, v178, v18
	v_dot4c_i32_i8_e32 v76, v182, v18
	v_dot4c_i32_i8_e32 v77, v186, v18
	v_dot4c_i32_i8_e32 v78, v192, v18
	v_dot4c_i32_i8_e32 v79, v196, v18
	v_dot4c_i32_i8_e32 v80, v200, v18
	v_dot4c_i32_i8_e32 v81, v204, v18
	v_dot4c_i32_i8_e32 v82, v208, v18
	v_dot4c_i32_i8_e32 v83, v212, v18
	v_dot4c_i32_i8_e32 v68, v151, v19
	v_dot4c_i32_i8_e32 v69, v155, v19
	v_dot4c_i32_i8_e32 v70, v159, v19
	v_dot4c_i32_i8_e32 v71, v163, v19
	v_dot4c_i32_i8_e32 v72, v167, v19
	v_dot4c_i32_i8_e32 v73, v171, v19
	v_dot4c_i32_i8_e32 v74, v175, v19
	v_dot4c_i32_i8_e32 v75, v179, v19
	v_dot4c_i32_i8_e32 v76, v183, v19
	v_dot4c_i32_i8_e32 v77, v187, v19
	v_dot4c_i32_i8_e32 v78, v193, v19
	v_dot4c_i32_i8_e32 v79, v197, v19
	v_dot4c_i32_i8_e32 v80, v201, v19
	v_dot4c_i32_i8_e32 v81, v205, v19
	v_dot4c_i32_i8_e32 v82, v209, v19
	v_dot4c_i32_i8_e32 v83, v213, v19
	v_lshl_add_u32 v36, v36, 11, v2
	v_lshl_add_u32 v37, v37, 11, v2
	v_lshl_add_u32 v38, v38, 11, v2
	v_lshl_add_u32 v39, v39, 11, v2
	v_lshl_add_u32 v40, v40, 11, v2
	v_lshl_add_u32 v41, v41, 11, v2
	v_lshl_add_u32 v42, v42, 11, v2
	v_lshl_add_u32 v43, v43, 11, v2
	v_lshl_add_u32 v44, v44, 11, v2
	v_lshl_add_u32 v45, v45, 11, v2
	v_lshl_add_u32 v46, v46, 11, v2
	v_lshl_add_u32 v47, v47, 11, v2
	v_lshl_add_u32 v48, v48, 11, v2
	v_lshl_add_u32 v49, v49, 11, v2
	v_lshl_add_u32 v50, v50, 11, v2
	v_lshl_add_u32 v51, v51, 11, v2
	global_load_dwordx4 v[148:151], v36, s[20:21]
	global_load_dwordx4 v[152:155], v37, s[20:21]
	global_load_dwordx4 v[156:159], v38, s[20:21]
	global_load_dwordx4 v[160:163], v39, s[20:21]
	global_load_dwordx4 v[164:167], v40, s[20:21]
	global_load_dwordx4 v[168:171], v41, s[20:21]
	global_load_dwordx4 v[172:175], v42, s[20:21]
	global_load_dwordx4 v[176:179], v43, s[20:21]
	global_load_dwordx4 v[180:183], v44, s[20:21]
	global_load_dwordx4 v[184:187], v45, s[20:21]
	global_load_dwordx4 v[190:193], v46, s[20:21]
	global_load_dwordx4 v[194:197], v47, s[20:21]
	global_load_dwordx4 v[198:201], v48, s[20:21]
	global_load_dwordx4 v[202:205], v49, s[20:21]
	global_load_dwordx4 v[206:209], v50, s[20:21]
	global_load_dwordx4 v[210:213], v51, s[20:21]
	v_add_u32_dpp v221, v68, v68 row_ror:8 row_mask:0xf bank_mask:0x3
	v_add_u32_dpp v221, v76, v76 row_ror:8 row_mask:0xf bank_mask:0xc
	v_add_u32_dpp v222, v69, v69 row_ror:8 row_mask:0xf bank_mask:0x3
	v_add_u32_dpp v222, v77, v77 row_ror:8 row_mask:0xf bank_mask:0xc
	v_add_u32_dpp v223, v70, v70 row_ror:8 row_mask:0xf bank_mask:0x3
	v_add_u32_dpp v223, v78, v78 row_ror:8 row_mask:0xf bank_mask:0xc
	v_add_u32_dpp v224, v71, v71 row_ror:8 row_mask:0xf bank_mask:0x3
	v_add_u32_dpp v224, v79, v79 row_ror:8 row_mask:0xf bank_mask:0xc
	v_add_u32_dpp v225, v72, v72 row_ror:8 row_mask:0xf bank_mask:0x3
	v_add_u32_dpp v225, v80, v80 row_ror:8 row_mask:0xf bank_mask:0xc
	v_add_u32_dpp v226, v73, v73 row_ror:8 row_mask:0xf bank_mask:0x3
	v_add_u32_dpp v226, v81, v81 row_ror:8 row_mask:0xf bank_mask:0xc
	v_add_u32_dpp v227, v74, v74 row_ror:8 row_mask:0xf bank_mask:0x3
	v_add_u32_dpp v227, v82, v82 row_ror:8 row_mask:0xf bank_mask:0xc
	v_add_u32_dpp v228, v75, v75 row_ror:8 row_mask:0xf bank_mask:0x3
	v_add_u32_dpp v228, v83, v83 row_ror:8 row_mask:0xf bank_mask:0xc
	v_add_u32_dpp v229, v221, v221 row_half_mirror row_mask:0xf bank_mask:0x5
	v_add_u32_dpp v229, v225, v225 row_half_mirror row_mask:0xf bank_mask:0xa
	v_add_u32_dpp v230, v222, v222 row_half_mirror row_mask:0xf bank_mask:0x5
	v_add_u32_dpp v230, v226, v226 row_half_mirror row_mask:0xf bank_mask:0xa
	v_add_u32_dpp v231, v223, v223 row_half_mirror row_mask:0xf bank_mask:0x5
	v_add_u32_dpp v231, v227, v227 row_half_mirror row_mask:0xf bank_mask:0xa
	v_add_u32_dpp v232, v224, v224 row_half_mirror row_mask:0xf bank_mask:0x5
	v_add_u32_dpp v232, v228, v228 row_half_mirror row_mask:0xf bank_mask:0xa
	v_add_u32_dpp v233, v229, v229 quad_perm:[2,3,0,1] row_mask:0xf bank_mask:0xf
	v_add_u32_dpp v234, v230, v230 quad_perm:[2,3,0,1] row_mask:0xf bank_mask:0xf
	v_add_u32_dpp v235, v231, v231 quad_perm:[2,3,0,1] row_mask:0xf bank_mask:0xf
	s_nop 0
	v_add_u32_dpp v236, v232, v232 quad_perm:[2,3,0,1] row_mask:0xf bank_mask:0xf
	v_cndmask_b32_e64 v237, v235, v233, s[2:3]
	v_cndmask_b32_e64 v238, v236, v234, s[2:3]
	s_nop 0
	s_nop 1
	v_add_u32_dpp v239, v237, v237 quad_perm:[1,0,3,2] row_mask:0xf bank_mask:0xf
	v_add_u32_dpp v240, v238, v238 quad_perm:[1,0,3,2] row_mask:0xf bank_mask:0xf
	v_cndmask_b32_e64 v241, v240, v239, s[4:5]
	global_store_dword v214, v241, s[14:15] offset:256
	s_add_i32 s36, s34, 2
	s_lshl_b32 s46, s36, 9
	s_add_i32 s46, s46, s24
	s_add_i32 s51, s48, 1
	s_add_i32 s56, s34, 4
	s_cmp_lt_u32 s51, s49
	s_cselect_b32 s56, s56, 8192
	s_cmp_lt_u32 s56, 8192
	s_cselect_b32 s57, 1, 0
	v_mov_b32_e32 v52, 0
	v_mov_b32_e32 v53, 0
	v_mov_b32_e32 v54, 0
	v_mov_b32_e32 v55, 0
	v_mov_b32_e32 v56, 0
	v_mov_b32_e32 v57, 0
	v_mov_b32_e32 v58, 0
	v_mov_b32_e32 v59, 0
	v_mov_b32_e32 v60, 0
	v_mov_b32_e32 v61, 0
	v_mov_b32_e32 v62, 0
	v_mov_b32_e32 v63, 0
	v_mov_b32_e32 v64, 0
	v_mov_b32_e32 v65, 0
	v_mov_b32_e32 v66, 0
	v_mov_b32_e32 v67, 0
	v_mov_b32_e32 v68, 0
	v_mov_b32_e32 v69, 0
	v_mov_b32_e32 v70, 0
	v_mov_b32_e32 v71, 0
	v_mov_b32_e32 v72, 0
	v_mov_b32_e32 v73, 0
	v_mov_b32_e32 v74, 0
	v_mov_b32_e32 v75, 0
	v_mov_b32_e32 v76, 0
	v_mov_b32_e32 v77, 0
	v_mov_b32_e32 v78, 0
	v_mov_b32_e32 v79, 0
	v_mov_b32_e32 v80, 0
	v_mov_b32_e32 v81, 0
	v_mov_b32_e32 v82, 0
	v_mov_b32_e32 v83, 0
	s_waitcnt vmcnt(33)
; DI void wave_lds_sync() { asm volatile("s_waitcnt lgkmcnt(0)" ::: "memory"); __builtin_amdgcn_wave_barrier(); }
; DI void phase9(const Params& p, char* smem, int rep) {
;     ...
;     for (int t = 0; t < 4; ++t) {
;       const int tok = __builtin_amdgcn_readfirstlane(c * 16 + w * 4 + t);
;       const int i0 = IDS[(size_t)tok * 128 + lane], i1 = IDS[(size_t)tok * 128 + 64 + lane];
;       const u32x4 hq = *(const u32x4*)(H2Q + (size_t)tok * D_ + s * 256 + l15 * 16);
;       wave_lds_sync();
;       lw[(lane & 3) * 32 + (lane >> 2)] = i0;
;       lw[(lane & 3) * 32 + 16 + (lane >> 2)] = i1;
;       wave_lds_sync();
;       const unsigned char* ub = U8 + s * 256 + l15 * 16;
; #pragma unroll
;       for (int batch = 0; batch < 2; ++batch) {
;         int ida[16];
; #pragma unroll
;         for (int q = 0; q < 4; ++q) { const int4 v = *(const int4*)(lw + g * 32 + batch * 16 + q * 4); ida[q * 4] = v.x; ida[q * 4 + 1] = v.y; ida[q * 4 + 2] = v.z; ida[q * 4 + 3] = v.w; }
;         u32x4 rows[16];
; #pragma unroll
;         for (int k = 0; k < 16; ++k) rows[k] = *(const u32x4*)(ub + (size_t)ida[k] * 2048);
;         int part[16];
; #pragma unroll
;         for (int k = 0; k < 16; ++k) {
;           int acc = 0;
; #pragma unroll
;           for (int d = 0; d < 4; ++d) acc = __builtin_amdgcn_sdot4((int)rows[k][d], (int)hq[d], acc, false);
;           part[k] = acc;
;         }
;         int q8[8], q4[4], q2[2];
; #pragma unroll
;         for (int k = 0; k < 8; ++k) q8[k] = (b3 ? part[8 + k] : part[k]) + __shfl_xor(b3 ? part[k] : part[8 + k], 8);
; #pragma unroll
;         for (int k = 0; k < 4; ++k) q4[k] = (b2 ? q8[4 + k] : q8[k]) + __shfl_xor(b2 ? q8[k] : q8[4 + k], 4);
; #pragma unroll
;         for (int k = 0; k < 2; ++k) q2[k] = (b1 ? q4[2 + k] : q4[k]) + __shfl_xor(b1 ? q4[k] : q4[2 + k], 2);
;         const int rr = (b0 ? q2[1] : q2[0]) + __shfl_xor(b0 ? q2[0] : q2[1], 1);
;         PA[((size_t)s * T_ + tok) * 128 + 4 * (batch * 16 + l15) + g] = rr;
;       }
	v_dot4c_i32_i8_e32 v52, v84, v12
	s_waitcnt vmcnt(32)
	v_dot4c_i32_i8_e32 v53, v88, v12
	s_waitcnt vmcnt(31)
	v_dot4c_i32_i8_e32 v54, v92, v12
	s_waitcnt vmcnt(30)
	v_dot4c_i32_i8_e32 v55, v96, v12
	s_waitcnt vmcnt(29)
	v_dot4c_i32_i8_e32 v56, v100, v12
	s_waitcnt vmcnt(28)
	v_dot4c_i32_i8_e32 v57, v104, v12
	s_waitcnt vmcnt(27)
	v_dot4c_i32_i8_e32 v58, v108, v12
	s_waitcnt vmcnt(26)
	v_dot4c_i32_i8_e32 v59, v112, v12
	s_waitcnt vmcnt(25)
	v_dot4c_i32_i8_e32 v60, v116, v12
	s_waitcnt vmcnt(24)
	v_dot4c_i32_i8_e32 v61, v120, v12
	s_waitcnt vmcnt(23)
	v_dot4c_i32_i8_e32 v62, v124, v12
	s_waitcnt vmcnt(22)
	v_dot4c_i32_i8_e32 v63, v128, v12
	s_waitcnt vmcnt(21)
	v_dot4c_i32_i8_e32 v64, v132, v12
	s_waitcnt vmcnt(20)
	v_dot4c_i32_i8_e32 v65, v136, v12
	s_waitcnt vmcnt(19)
	v_dot4c_i32_i8_e32 v66, v140, v12
	s_waitcnt vmcnt(18)
	v_dot4c_i32_i8_e32 v67, v144, v12
	v_dot4c_i32_i8_e32 v52, v85, v13
	v_dot4c_i32_i8_e32 v53, v89, v13
	v_dot4c_i32_i8_e32 v54, v93, v13
	v_dot4c_i32_i8_e32 v55, v97, v13
	v_dot4c_i32_i8_e32 v56, v101, v13
	v_dot4c_i32_i8_e32 v57, v105, v13
	v_dot4c_i32_i8_e32 v58, v109, v13
	v_dot4c_i32_i8_e32 v59, v113, v13
	v_dot4c_i32_i8_e32 v60, v117, v13
	v_dot4c_i32_i8_e32 v61, v121, v13
	v_dot4c_i32_i8_e32 v62, v125, v13
	v_dot4c_i32_i8_e32 v63, v129, v13
	v_dot4c_i32_i8_e32 v64, v133, v13
	v_dot4c_i32_i8_e32 v65, v137, v13
	v_dot4c_i32_i8_e32 v66, v141, v13
	v_dot4c_i32_i8_e32 v67, v145, v13
	v_dot4c_i32_i8_e32 v52, v86, v14
	v_dot4c_i32_i8_e32 v53, v90, v14
	v_dot4c_i32_i8_e32 v54, v94, v14
	v_dot4c_i32_i8_e32 v55, v98, v14
	v_dot4c_i32_i8_e32 v56, v102, v14
	v_dot4c_i32_i8_e32 v57, v106, v14
	v_dot4c_i32_i8_e32 v58, v110, v14
	v_dot4c_i32_i8_e32 v59, v114, v14
	v_dot4c_i32_i8_e32 v60, v118, v14
	v_dot4c_i32_i8_e32 v61, v122, v14
	v_dot4c_i32_i8_e32 v62, v126, v14
	v_dot4c_i32_i8_e32 v63, v130, v14
	v_dot4c_i32_i8_e32 v64, v134, v14
	v_dot4c_i32_i8_e32 v65, v138, v14
	v_dot4c_i32_i8_e32 v66, v142, v14
	v_dot4c_i32_i8_e32 v67, v146, v14
	v_dot4c_i32_i8_e32 v52, v87, v15
	v_dot4c_i32_i8_e32 v53, v91, v15
	v_dot4c_i32_i8_e32 v54, v95, v15
	v_dot4c_i32_i8_e32 v55, v99, v15
	v_dot4c_i32_i8_e32 v56, v103, v15
	v_dot4c_i32_i8_e32 v57, v107, v15
	v_dot4c_i32_i8_e32 v58, v111, v15
	v_dot4c_i32_i8_e32 v59, v115, v15
	v_dot4c_i32_i8_e32 v60, v119, v15
	v_dot4c_i32_i8_e32 v61, v123, v15
	v_dot4c_i32_i8_e32 v62, v127, v15
	v_dot4c_i32_i8_e32 v63, v131, v15
	v_dot4c_i32_i8_e32 v64, v135, v15
	v_dot4c_i32_i8_e32 v65, v139, v15
	v_dot4c_i32_i8_e32 v66, v143, v15
	v_dot4c_i32_i8_e32 v67, v147, v15
	ds_write2_b32 v5, v10, v11 offset0:4 offset1:20
	s_waitcnt lgkmcnt(0)
	ds_read_b128 v[20:23], v6 offset:16
	ds_read_b128 v[24:27], v6 offset:32
	ds_read_b128 v[28:31], v6 offset:48
	ds_read_b128 v[32:35], v6 offset:64
	ds_read_b128 v[36:39], v6 offset:80
	ds_read_b128 v[40:43], v6 offset:96
	ds_read_b128 v[44:47], v6 offset:112
	ds_read_b128 v[48:51], v6 offset:128
	s_add_i32 s37, s56, 0
	s_cmp_eq_u32 s57, 1
	s_cselect_b32 s37, s37, 0
	s_lshl_b32 s47, s37, 9
	s_add_u32 s42, s6, s47
	s_addc_u32 s43, s7, 0
	global_load_dword v10, v3, s[42:43]
	global_load_dword v11, v3, s[42:43] offset:256
	s_add_i32 s37, s34, 3
	s_lshl_b32 s47, s37, 11
	s_add_u32 s44, s22, s47
	s_addc_u32 s45, s23, 0
	global_load_dwordx4 v[16:19], v2, s[44:45]
	s_waitcnt lgkmcnt(0)
	v_lshl_add_u32 v20, v20, 11, v2
	v_lshl_add_u32 v21, v21, 11, v2
	v_lshl_add_u32 v22, v22, 11, v2
	v_lshl_add_u32 v23, v23, 11, v2
	v_lshl_add_u32 v24, v24, 11, v2
	v_lshl_add_u32 v25, v25, 11, v2
	v_lshl_add_u32 v26, v26, 11, v2
	v_lshl_add_u32 v27, v27, 11, v2
	v_lshl_add_u32 v28, v28, 11, v2
	v_lshl_add_u32 v29, v29, 11, v2
	v_lshl_add_u32 v30, v30, 11, v2
	v_lshl_add_u32 v31, v31, 11, v2
	v_lshl_add_u32 v32, v32, 11, v2
	v_lshl_add_u32 v33, v33, 11, v2
	v_lshl_add_u32 v34, v34, 11, v2
	v_lshl_add_u32 v35, v35, 11, v2
	global_load_dwordx4 v[84:87], v20, s[20:21]
	global_load_dwordx4 v[88:91], v21, s[20:21]
	global_load_dwordx4 v[92:95], v22, s[20:21]
	global_load_dwordx4 v[96:99], v23, s[20:21]
	global_load_dwordx4 v[100:103], v24, s[20:21]
	global_load_dwordx4 v[104:107], v25, s[20:21]
	global_load_dwordx4 v[108:111], v26, s[20:21]
	global_load_dwordx4 v[112:115], v27, s[20:21]
	global_load_dwordx4 v[116:119], v28, s[20:21]
	global_load_dwordx4 v[120:123], v29, s[20:21]
	global_load_dwordx4 v[124:127], v30, s[20:21]
	global_load_dwordx4 v[128:131], v31, s[20:21]
	global_load_dwordx4 v[132:135], v32, s[20:21]
	global_load_dwordx4 v[136:139], v33, s[20:21]
	global_load_dwordx4 v[140:143], v34, s[20:21]
	global_load_dwordx4 v[144:147], v35, s[20:21]
	v_add_u32_dpp v221, v52, v52 row_ror:8 row_mask:0xf bank_mask:0x3
	v_add_u32_dpp v221, v60, v60 row_ror:8 row_mask:0xf bank_mask:0xc
	v_add_u32_dpp v222, v53, v53 row_ror:8 row_mask:0xf bank_mask:0x3
	v_add_u32_dpp v222, v61, v61 row_ror:8 row_mask:0xf bank_mask:0xc
	v_add_u32_dpp v223, v54, v54 row_ror:8 row_mask:0xf bank_mask:0x3
	v_add_u32_dpp v223, v62, v62 row_ror:8 row_mask:0xf bank_mask:0xc
	v_add_u32_dpp v224, v55, v55 row_ror:8 row_mask:0xf bank_mask:0x3
	v_add_u32_dpp v224, v63, v63 row_ror:8 row_mask:0xf bank_mask:0xc
	v_add_u32_dpp v225, v56, v56 row_ror:8 row_mask:0xf bank_mask:0x3
	v_add_u32_dpp v225, v64, v64 row_ror:8 row_mask:0xf bank_mask:0xc
	v_add_u32_dpp v226, v57, v57 row_ror:8 row_mask:0xf bank_mask:0x3
	v_add_u32_dpp v226, v65, v65 row_ror:8 row_mask:0xf bank_mask:0xc
	v_add_u32_dpp v227, v58, v58 row_ror:8 row_mask:0xf bank_mask:0x3
	v_add_u32_dpp v227, v66, v66 row_ror:8 row_mask:0xf bank_mask:0xc
	v_add_u32_dpp v228, v59, v59 row_ror:8 row_mask:0xf bank_mask:0x3
	v_add_u32_dpp v228, v67, v67 row_ror:8 row_mask:0xf bank_mask:0xc
	v_add_u32_dpp v229, v221, v221 row_half_mirror row_mask:0xf bank_mask:0x5
	v_add_u32_dpp v229, v225, v225 row_half_mirror row_mask:0xf bank_mask:0xa
	v_add_u32_dpp v230, v222, v222 row_half_mirror row_mask:0xf bank_mask:0x5
	v_add_u32_dpp v230, v226, v226 row_half_mirror row_mask:0xf bank_mask:0xa
	v_add_u32_dpp v231, v223, v223 row_half_mirror row_mask:0xf bank_mask:0x5
	v_add_u32_dpp v231, v227, v227 row_half_mirror row_mask:0xf bank_mask:0xa
	v_add_u32_dpp v232, v224, v224 row_half_mirror row_mask:0xf bank_mask:0x5
	v_add_u32_dpp v232, v228, v228 row_half_mirror row_mask:0xf bank_mask:0xa
	v_add_u32_dpp v233, v229, v229 quad_perm:[2,3,0,1] row_mask:0xf bank_mask:0xf
	v_add_u32_dpp v234, v230, v230 quad_perm:[2,3,0,1] row_mask:0xf bank_mask:0xf
	v_add_u32_dpp v235, v231, v231 quad_perm:[2,3,0,1] row_mask:0xf bank_mask:0xf
	s_nop 0
	v_add_u32_dpp v236, v232, v232 quad_perm:[2,3,0,1] row_mask:0xf bank_mask:0xf
	v_cndmask_b32_e64 v237, v235, v233, s[2:3]
	v_cndmask_b32_e64 v238, v236, v234, s[2:3]
	v_add_u32_e32 v214, s46, v4
	s_nop 1
	v_add_u32_dpp v239, v237, v237 quad_perm:[1,0,3,2] row_mask:0xf bank_mask:0xf
	v_add_u32_dpp v240, v238, v238 quad_perm:[1,0,3,2] row_mask:0xf bank_mask:0xf
	v_cndmask_b32_e64 v241, v240, v239, s[4:5]
	global_store_dword v214, v241, s[14:15]
	s_waitcnt vmcnt(36)
; DI void phase9(const Params& p, char* smem, int rep) {
;     ...
;         for (int q = 0; q < 4; ++q) { const int4 v = *(const int4*)(lw + g * 32 + batch * 16 + q * 4); ida[q * 4] = v.x; ida[q * 4 + 1] = v.y; ida[q * 4 + 2] = v.z; ida[q * 4 + 3] = v.w; }
;         u32x4 rows[16];
; #pragma unroll
;         for (int k = 0; k < 16; ++k) rows[k] = *(const u32x4*)(ub + (size_t)ida[k] * 2048);
;         int part[16];
; #pragma unroll
;         for (int k = 0; k < 16; ++k) {
;           int acc = 0;
; #pragma unroll
;           for (int d = 0; d < 4; ++d) acc = __builtin_amdgcn_sdot4((int)rows[k][d], (int)hq[d], acc, false);
;           part[k] = acc;
;         }
;         int q8[8], q4[4], q2[2];
; #pragma unroll
;         for (int k = 0; k < 8; ++k) q8[k] = (b3 ? part[8 + k] : part[k]) + __shfl_xor(b3 ? part[k] : part[8 + k], 8);
; #pragma unroll
;         for (int k = 0; k < 4; ++k) q4[k] = (b2 ? q8[4 + k] : q8[k]) + __shfl_xor(b2 ? q8[k] : q8[4 + k], 4);
; #pragma unroll
;         for (int k = 0; k < 2; ++k) q2[k] = (b1 ? q4[2 + k] : q4[k]) + __shfl_xor(b1 ? q4[k] : q4[2 + k], 2);
;         const int rr = (b0 ? q2[1] : q2[0]) + __shfl_xor(b0 ? q2[0] : q2[1], 1);
;         PA[((size_t)s * T_ + tok) * 128 + 4 * (batch * 16 + l15) + g] = rr;
;       }
	v_dot4c_i32_i8_e32 v68, v148, v12
	s_waitcnt vmcnt(35)
	v_dot4c_i32_i8_e32 v69, v152, v12
	s_waitcnt vmcnt(34)
	v_dot4c_i32_i8_e32 v70, v156, v12
	s_waitcnt vmcnt(33)
	v_dot4c_i32_i8_e32 v71, v160, v12
	s_waitcnt vmcnt(32)
	v_dot4c_i32_i8_e32 v72, v164, v12
	s_waitcnt vmcnt(31)
	v_dot4c_i32_i8_e32 v73, v168, v12
	s_waitcnt vmcnt(30)
	v_dot4c_i32_i8_e32 v74, v172, v12
	s_waitcnt vmcnt(29)
	v_dot4c_i32_i8_e32 v75, v176, v12
	s_waitcnt vmcnt(28)
	v_dot4c_i32_i8_e32 v76, v180, v12
	s_waitcnt vmcnt(27)
	v_dot4c_i32_i8_e32 v77, v184, v12
	s_waitcnt vmcnt(26)
	v_dot4c_i32_i8_e32 v78, v190, v12
	s_waitcnt vmcnt(25)
	v_dot4c_i32_i8_e32 v79, v194, v12
	s_waitcnt vmcnt(24)
	v_dot4c_i32_i8_e32 v80, v198, v12
	s_waitcnt vmcnt(23)
	v_dot4c_i32_i8_e32 v81, v202, v12
	s_waitcnt vmcnt(22)
	v_dot4c_i32_i8_e32 v82, v206, v12
	s_waitcnt vmcnt(21)
	v_dot4c_i32_i8_e32 v83, v210, v12
	v_dot4c_i32_i8_e32 v68, v149, v13
	v_dot4c_i32_i8_e32 v69, v153, v13
	v_dot4c_i32_i8_e32 v70, v157, v13
	v_dot4c_i32_i8_e32 v71, v161, v13
	v_dot4c_i32_i8_e32 v72, v165, v13
	v_dot4c_i32_i8_e32 v73, v169, v13
	v_dot4c_i32_i8_e32 v74, v173, v13
	v_dot4c_i32_i8_e32 v75, v177, v13
	v_dot4c_i32_i8_e32 v76, v181, v13
	v_dot4c_i32_i8_e32 v77, v185, v13
	v_dot4c_i32_i8_e32 v78, v191, v13
	v_dot4c_i32_i8_e32 v79, v195, v13
	v_dot4c_i32_i8_e32 v80, v199, v13
	v_dot4c_i32_i8_e32 v81, v203, v13
	v_dot4c_i32_i8_e32 v82, v207, v13
	v_dot4c_i32_i8_e32 v83, v211, v13
	v_dot4c_i32_i8_e32 v68, v150, v14
	v_dot4c_i32_i8_e32 v69, v154, v14
	v_dot4c_i32_i8_e32 v70, v158, v14
	v_dot4c_i32_i8_e32 v71, v162, v14
	v_dot4c_i32_i8_e32 v72, v166, v14
	v_dot4c_i32_i8_e32 v73, v170, v14
	v_dot4c_i32_i8_e32 v74, v174, v14
	v_dot4c_i32_i8_e32 v75, v178, v14
	v_dot4c_i32_i8_e32 v76, v182, v14
	v_dot4c_i32_i8_e32 v77, v186, v14
	v_dot4c_i32_i8_e32 v78, v192, v14
	v_dot4c_i32_i8_e32 v79, v196, v14
	v_dot4c_i32_i8_e32 v80, v200, v14
	v_dot4c_i32_i8_e32 v81, v204, v14
	v_dot4c_i32_i8_e32 v82, v208, v14
	v_dot4c_i32_i8_e32 v83, v212, v14
	v_dot4c_i32_i8_e32 v68, v151, v15
	v_dot4c_i32_i8_e32 v69, v155, v15
	v_dot4c_i32_i8_e32 v70, v159, v15
	v_dot4c_i32_i8_e32 v71, v163, v15
	v_dot4c_i32_i8_e32 v72, v167, v15
	v_dot4c_i32_i8_e32 v73, v171, v15
	v_dot4c_i32_i8_e32 v74, v175, v15
	v_dot4c_i32_i8_e32 v75, v179, v15
	v_dot4c_i32_i8_e32 v76, v183, v15
	v_dot4c_i32_i8_e32 v77, v187, v15
	v_dot4c_i32_i8_e32 v78, v193, v15
	v_dot4c_i32_i8_e32 v79, v197, v15
	v_dot4c_i32_i8_e32 v80, v201, v15
	v_dot4c_i32_i8_e32 v81, v205, v15
	v_dot4c_i32_i8_e32 v82, v209, v15
	v_dot4c_i32_i8_e32 v83, v213, v15
	v_lshl_add_u32 v36, v36, 11, v2
	v_lshl_add_u32 v37, v37, 11, v2
	v_lshl_add_u32 v38, v38, 11, v2
	v_lshl_add_u32 v39, v39, 11, v2
	v_lshl_add_u32 v40, v40, 11, v2
	v_lshl_add_u32 v41, v41, 11, v2
	v_lshl_add_u32 v42, v42, 11, v2
	v_lshl_add_u32 v43, v43, 11, v2
	v_lshl_add_u32 v44, v44, 11, v2
	v_lshl_add_u32 v45, v45, 11, v2
	v_lshl_add_u32 v46, v46, 11, v2
	v_lshl_add_u32 v47, v47, 11, v2
	v_lshl_add_u32 v48, v48, 11, v2
	v_lshl_add_u32 v49, v49, 11, v2
	v_lshl_add_u32 v50, v50, 11, v2
	v_lshl_add_u32 v51, v51, 11, v2
	global_load_dwordx4 v[148:151], v36, s[20:21]
	global_load_dwordx4 v[152:155], v37, s[20:21]
	global_load_dwordx4 v[156:159], v38, s[20:21]
	global_load_dwordx4 v[160:163], v39, s[20:21]
	global_load_dwordx4 v[164:167], v40, s[20:21]
	global_load_dwordx4 v[168:171], v41, s[20:21]
	global_load_dwordx4 v[172:175], v42, s[20:21]
	global_load_dwordx4 v[176:179], v43, s[20:21]
	global_load_dwordx4 v[180:183], v44, s[20:21]
	global_load_dwordx4 v[184:187], v45, s[20:21]
	global_load_dwordx4 v[190:193], v46, s[20:21]
	global_load_dwordx4 v[194:197], v47, s[20:21]
	global_load_dwordx4 v[198:201], v48, s[20:21]
	global_load_dwordx4 v[202:205], v49, s[20:21]
	global_load_dwordx4 v[206:209], v50, s[20:21]
	global_load_dwordx4 v[210:213], v51, s[20:21]
	v_add_u32_dpp v221, v68, v68 row_ror:8 row_mask:0xf bank_mask:0x3
	v_add_u32_dpp v221, v76, v76 row_ror:8 row_mask:0xf bank_mask:0xc
	v_add_u32_dpp v222, v69, v69 row_ror:8 row_mask:0xf bank_mask:0x3
	v_add_u32_dpp v222, v77, v77 row_ror:8 row_mask:0xf bank_mask:0xc
	v_add_u32_dpp v223, v70, v70 row_ror:8 row_mask:0xf bank_mask:0x3
	v_add_u32_dpp v223, v78, v78 row_ror:8 row_mask:0xf bank_mask:0xc
	v_add_u32_dpp v224, v71, v71 row_ror:8 row_mask:0xf bank_mask:0x3
	v_add_u32_dpp v224, v79, v79 row_ror:8 row_mask:0xf bank_mask:0xc
	v_add_u32_dpp v225, v72, v72 row_ror:8 row_mask:0xf bank_mask:0x3
	v_add_u32_dpp v225, v80, v80 row_ror:8 row_mask:0xf bank_mask:0xc
	v_add_u32_dpp v226, v73, v73 row_ror:8 row_mask:0xf bank_mask:0x3
	v_add_u32_dpp v226, v81, v81 row_ror:8 row_mask:0xf bank_mask:0xc
	v_add_u32_dpp v227, v74, v74 row_ror:8 row_mask:0xf bank_mask:0x3
	v_add_u32_dpp v227, v82, v82 row_ror:8 row_mask:0xf bank_mask:0xc
	v_add_u32_dpp v228, v75, v75 row_ror:8 row_mask:0xf bank_mask:0x3
	v_add_u32_dpp v228, v83, v83 row_ror:8 row_mask:0xf bank_mask:0xc
	v_add_u32_dpp v229, v221, v221 row_half_mirror row_mask:0xf bank_mask:0x5
	v_add_u32_dpp v229, v225, v225 row_half_mirror row_mask:0xf bank_mask:0xa
	v_add_u32_dpp v230, v222, v222 row_half_mirror row_mask:0xf bank_mask:0x5
	v_add_u32_dpp v230, v226, v226 row_half_mirror row_mask:0xf bank_mask:0xa
	v_add_u32_dpp v231, v223, v223 row_half_mirror row_mask:0xf bank_mask:0x5
	v_add_u32_dpp v231, v227, v227 row_half_mirror row_mask:0xf bank_mask:0xa
	v_add_u32_dpp v232, v224, v224 row_half_mirror row_mask:0xf bank_mask:0x5
	v_add_u32_dpp v232, v228, v228 row_half_mirror row_mask:0xf bank_mask:0xa
	v_add_u32_dpp v233, v229, v229 quad_perm:[2,3,0,1] row_mask:0xf bank_mask:0xf
	v_add_u32_dpp v234, v230, v230 quad_perm:[2,3,0,1] row_mask:0xf bank_mask:0xf
; DI void wave_lds_sync() { asm volatile("s_waitcnt lgkmcnt(0)" ::: "memory"); __builtin_amdgcn_wave_barrier(); }
; DI void phase9(const Params& p, char* smem, int rep) {
;     ...
;     for (int t = 0; t < 4; ++t) {
;       const int tok = __builtin_amdgcn_readfirstlane(c * 16 + w * 4 + t);
;       const int i0 = IDS[(size_t)tok * 128 + lane], i1 = IDS[(size_t)tok * 128 + 64 + lane];
;       const u32x4 hq = *(const u32x4*)(H2Q + (size_t)tok * D_ + s * 256 + l15 * 16);
;       wave_lds_sync();
;       lw[(lane & 3) * 32 + (lane >> 2)] = i0;
;       lw[(lane & 3) * 32 + 16 + (lane >> 2)] = i1;
;       wave_lds_sync();
;       const unsigned char* ub = U8 + s * 256 + l15 * 16;
; #pragma unroll
;       for (int batch = 0; batch < 2; ++batch) {
;         int ida[16];
; #pragma unroll
;         for (int q = 0; q < 4; ++q) { const int4 v = *(const int4*)(lw + g * 32 + batch * 16 + q * 4); ida[q * 4] = v.x; ida[q * 4 + 1] = v.y; ida[q * 4 + 2] = v.z; ida[q * 4 + 3] = v.w; }
;         u32x4 rows[16];
; #pragma unroll
;         for (int k = 0; k < 16; ++k) rows[k] = *(const u32x4*)(ub + (size_t)ida[k] * 2048);
;         int part[16];
; #pragma unroll
;         for (int k = 0; k < 16; ++k) {
;           int acc = 0;
; #pragma unroll
;           for (int d = 0; d < 4; ++d) acc = __builtin_amdgcn_sdot4((int)rows[k][d], (int)hq[d], acc, false);
;           part[k] = acc;
;         }
;         int q8[8], q4[4], q2[2];
; #pragma unroll
;         for (int k = 0; k < 8; ++k) q8[k] = (b3 ? part[8 + k] : part[k]) + __shfl_xor(b3 ? part[k] : part[8 + k], 8);
; #pragma unroll
;         for (int k = 0; k < 4; ++k) q4[k] = (b2 ? q8[4 + k] : q8[k]) + __shfl_xor(b2 ? q8[k] : q8[4 + k], 4);
; #pragma unroll
;         for (int k = 0; k < 2; ++k) q2[k] = (b1 ? q4[2 + k] : q4[k]) + __shfl_xor(b1 ? q4[k] : q4[2 + k], 2);
;         const int rr = (b0 ? q2[1] : q2[0]) + __shfl_xor(b0 ? q2[0] : q2[1], 1);
;         PA[((size_t)s * T_ + tok) * 128 + 4 * (batch * 16 + l15) + g] = rr;
;       }
	v_add_u32_dpp v235, v231, v231 quad_perm:[2,3,0,1] row_mask:0xf bank_mask:0xf
	s_nop 0
	v_add_u32_dpp v236, v232, v232 quad_perm:[2,3,0,1] row_mask:0xf bank_mask:0xf
	v_cndmask_b32_e64 v237, v235, v233, s[2:3]
	v_cndmask_b32_e64 v238, v236, v234, s[2:3]
	s_nop 0
	s_nop 1
	v_add_u32_dpp v239, v237, v237 quad_perm:[1,0,3,2] row_mask:0xf bank_mask:0xf
	v_add_u32_dpp v240, v238, v238 quad_perm:[1,0,3,2] row_mask:0xf bank_mask:0xf
	v_cndmask_b32_e64 v241, v240, v239, s[4:5]
	global_store_dword v214, v241, s[14:15] offset:256
	s_add_i32 s36, s34, 3
	s_lshl_b32 s46, s36, 9
	s_add_i32 s46, s46, s24
	s_add_i32 s51, s48, 1
	s_add_i32 s56, s34, 4
	s_cmp_lt_u32 s51, s49
	s_cselect_b32 s56, s56, 8192
	s_cmp_lt_u32 s56, 8192
	s_cselect_b32 s57, 1, 0
	v_mov_b32_e32 v52, 0
	v_mov_b32_e32 v53, 0
	v_mov_b32_e32 v54, 0
	v_mov_b32_e32 v55, 0
	v_mov_b32_e32 v56, 0
	v_mov_b32_e32 v57, 0
	v_mov_b32_e32 v58, 0
	v_mov_b32_e32 v59, 0
	v_mov_b32_e32 v60, 0
	v_mov_b32_e32 v61, 0
	v_mov_b32_e32 v62, 0
	v_mov_b32_e32 v63, 0
	v_mov_b32_e32 v64, 0
	v_mov_b32_e32 v65, 0
	v_mov_b32_e32 v66, 0
	v_mov_b32_e32 v67, 0
	v_mov_b32_e32 v68, 0
	v_mov_b32_e32 v69, 0
	v_mov_b32_e32 v70, 0
	v_mov_b32_e32 v71, 0
	v_mov_b32_e32 v72, 0
	v_mov_b32_e32 v73, 0
	v_mov_b32_e32 v74, 0
	v_mov_b32_e32 v75, 0
	v_mov_b32_e32 v76, 0
	v_mov_b32_e32 v77, 0
	v_mov_b32_e32 v78, 0
	v_mov_b32_e32 v79, 0
	v_mov_b32_e32 v80, 0
	v_mov_b32_e32 v81, 0
	v_mov_b32_e32 v82, 0
	v_mov_b32_e32 v83, 0
	s_waitcnt vmcnt(33)
	v_dot4c_i32_i8_e32 v52, v84, v16
	s_waitcnt vmcnt(32)
	v_dot4c_i32_i8_e32 v53, v88, v16
	s_waitcnt vmcnt(31)
	v_dot4c_i32_i8_e32 v54, v92, v16
	s_waitcnt vmcnt(30)
	v_dot4c_i32_i8_e32 v55, v96, v16
	s_waitcnt vmcnt(29)
	v_dot4c_i32_i8_e32 v56, v100, v16
	s_waitcnt vmcnt(28)
	v_dot4c_i32_i8_e32 v57, v104, v16
	s_waitcnt vmcnt(27)
	v_dot4c_i32_i8_e32 v58, v108, v16
	s_waitcnt vmcnt(26)
	v_dot4c_i32_i8_e32 v59, v112, v16
	s_waitcnt vmcnt(25)
	v_dot4c_i32_i8_e32 v60, v116, v16
	s_waitcnt vmcnt(24)
	v_dot4c_i32_i8_e32 v61, v120, v16
	s_waitcnt vmcnt(23)
	v_dot4c_i32_i8_e32 v62, v124, v16
	s_waitcnt vmcnt(22)
	v_dot4c_i32_i8_e32 v63, v128, v16
	s_waitcnt vmcnt(21)
	v_dot4c_i32_i8_e32 v64, v132, v16
	s_waitcnt vmcnt(20)
	v_dot4c_i32_i8_e32 v65, v136, v16
	s_waitcnt vmcnt(19)
	v_dot4c_i32_i8_e32 v66, v140, v16
	s_waitcnt vmcnt(18)
	v_dot4c_i32_i8_e32 v67, v144, v16
	v_dot4c_i32_i8_e32 v52, v85, v17
	v_dot4c_i32_i8_e32 v53, v89, v17
	v_dot4c_i32_i8_e32 v54, v93, v17
	v_dot4c_i32_i8_e32 v55, v97, v17
	v_dot4c_i32_i8_e32 v56, v101, v17
	v_dot4c_i32_i8_e32 v57, v105, v17
	v_dot4c_i32_i8_e32 v58, v109, v17
	v_dot4c_i32_i8_e32 v59, v113, v17
	v_dot4c_i32_i8_e32 v60, v117, v17
	v_dot4c_i32_i8_e32 v61, v121, v17
	v_dot4c_i32_i8_e32 v62, v125, v17
	v_dot4c_i32_i8_e32 v63, v129, v17
	v_dot4c_i32_i8_e32 v64, v133, v17
	v_dot4c_i32_i8_e32 v65, v137, v17
	v_dot4c_i32_i8_e32 v66, v141, v17
	v_dot4c_i32_i8_e32 v67, v145, v17
	v_dot4c_i32_i8_e32 v52, v86, v18
	v_dot4c_i32_i8_e32 v53, v90, v18
	v_dot4c_i32_i8_e32 v54, v94, v18
	v_dot4c_i32_i8_e32 v55, v98, v18
	v_dot4c_i32_i8_e32 v56, v102, v18
	v_dot4c_i32_i8_e32 v57, v106, v18
	v_dot4c_i32_i8_e32 v58, v110, v18
	v_dot4c_i32_i8_e32 v59, v114, v18
	v_dot4c_i32_i8_e32 v60, v118, v18
	v_dot4c_i32_i8_e32 v61, v122, v18
	v_dot4c_i32_i8_e32 v62, v126, v18
	v_dot4c_i32_i8_e32 v63, v130, v18
	v_dot4c_i32_i8_e32 v64, v134, v18
	v_dot4c_i32_i8_e32 v65, v138, v18
	v_dot4c_i32_i8_e32 v66, v142, v18
	v_dot4c_i32_i8_e32 v67, v146, v18
	v_dot4c_i32_i8_e32 v52, v87, v19
	v_dot4c_i32_i8_e32 v53, v91, v19
	v_dot4c_i32_i8_e32 v54, v95, v19
	v_dot4c_i32_i8_e32 v55, v99, v19
	v_dot4c_i32_i8_e32 v56, v103, v19
	v_dot4c_i32_i8_e32 v57, v107, v19
	v_dot4c_i32_i8_e32 v58, v111, v19
	v_dot4c_i32_i8_e32 v59, v115, v19
	v_dot4c_i32_i8_e32 v60, v119, v19
	v_dot4c_i32_i8_e32 v61, v123, v19
	v_dot4c_i32_i8_e32 v62, v127, v19
	v_dot4c_i32_i8_e32 v63, v131, v19
	v_dot4c_i32_i8_e32 v64, v135, v19
	v_dot4c_i32_i8_e32 v65, v139, v19
	v_dot4c_i32_i8_e32 v66, v143, v19
	v_dot4c_i32_i8_e32 v67, v147, v19
	ds_write2_b32 v5, v10, v11 offset0:4 offset1:20
	s_waitcnt lgkmcnt(0)
	ds_read_b128 v[20:23], v6 offset:16
	ds_read_b128 v[24:27], v6 offset:32
	ds_read_b128 v[28:31], v6 offset:48
	ds_read_b128 v[32:35], v6 offset:64
	ds_read_b128 v[36:39], v6 offset:80
	ds_read_b128 v[40:43], v6 offset:96
	ds_read_b128 v[44:47], v6 offset:112
	ds_read_b128 v[48:51], v6 offset:128
	s_add_i32 s37, s56, 1
	s_cmp_eq_u32 s57, 1
	s_cselect_b32 s37, s37, 1
	s_lshl_b32 s47, s37, 9
	s_add_u32 s42, s6, s47
	s_addc_u32 s43, s7, 0
	global_load_dword v10, v3, s[42:43]
	global_load_dword v11, v3, s[42:43] offset:256
	s_add_i32 s37, s56, 0
	s_cmp_eq_u32 s57, 1
	s_cselect_b32 s37, s37, 0
	s_lshl_b32 s47, s37, 11
	s_add_u32 s44, s22, s47
	s_addc_u32 s45, s23, 0
	global_load_dwordx4 v[12:15], v2, s[44:45]
	s_waitcnt lgkmcnt(0)
; DI void phase9(const Params& p, char* smem, int rep) {
;     ...
;         for (int q = 0; q < 4; ++q) { const int4 v = *(const int4*)(lw + g * 32 + batch * 16 + q * 4); ida[q * 4] = v.x; ida[q * 4 + 1] = v.y; ida[q * 4 + 2] = v.z; ida[q * 4 + 3] = v.w; }
;         u32x4 rows[16];
; #pragma unroll
;         for (int k = 0; k < 16; ++k) rows[k] = *(const u32x4*)(ub + (size_t)ida[k] * 2048);
;         int part[16];
; #pragma unroll
;         for (int k = 0; k < 16; ++k) {
;           int acc = 0;
; #pragma unroll
;           for (int d = 0; d < 4; ++d) acc = __builtin_amdgcn_sdot4((int)rows[k][d], (int)hq[d], acc, false);
;           part[k] = acc;
;         }
;         int q8[8], q4[4], q2[2];
; #pragma unroll
;         for (int k = 0; k < 8; ++k) q8[k] = (b3 ? part[8 + k] : part[k]) + __shfl_xor(b3 ? part[k] : part[8 + k], 8);
; #pragma unroll
;         for (int k = 0; k < 4; ++k) q4[k] = (b2 ? q8[4 + k] : q8[k]) + __shfl_xor(b2 ? q8[k] : q8[4 + k], 4);
; #pragma unroll
;         for (int k = 0; k < 2; ++k) q2[k] = (b1 ? q4[2 + k] : q4[k]) + __shfl_xor(b1 ? q4[k] : q4[2 + k], 2);
;         const int rr = (b0 ? q2[1] : q2[0]) + __shfl_xor(b0 ? q2[0] : q2[1], 1);
;         PA[((size_t)s * T_ + tok) * 128 + 4 * (batch * 16 + l15) + g] = rr;
;       }
	v_lshl_add_u32 v20, v20, 11, v2
	v_lshl_add_u32 v21, v21, 11, v2
	v_lshl_add_u32 v22, v22, 11, v2
	v_lshl_add_u32 v23, v23, 11, v2
	v_lshl_add_u32 v24, v24, 11, v2
	v_lshl_add_u32 v25, v25, 11, v2
	v_lshl_add_u32 v26, v26, 11, v2
	v_lshl_add_u32 v27, v27, 11, v2
	v_lshl_add_u32 v28, v28, 11, v2
	v_lshl_add_u32 v29, v29, 11, v2
	v_lshl_add_u32 v30, v30, 11, v2
	v_lshl_add_u32 v31, v31, 11, v2
	v_lshl_add_u32 v32, v32, 11, v2
	v_lshl_add_u32 v33, v33, 11, v2
	v_lshl_add_u32 v34, v34, 11, v2
	v_lshl_add_u32 v35, v35, 11, v2
	global_load_dwordx4 v[84:87], v20, s[20:21]
	global_load_dwordx4 v[88:91], v21, s[20:21]
	global_load_dwordx4 v[92:95], v22, s[20:21]
	global_load_dwordx4 v[96:99], v23, s[20:21]
	global_load_dwordx4 v[100:103], v24, s[20:21]
	global_load_dwordx4 v[104:107], v25, s[20:21]
	global_load_dwordx4 v[108:111], v26, s[20:21]
	global_load_dwordx4 v[112:115], v27, s[20:21]
	global_load_dwordx4 v[116:119], v28, s[20:21]
	global_load_dwordx4 v[120:123], v29, s[20:21]
	global_load_dwordx4 v[124:127], v30, s[20:21]
	global_load_dwordx4 v[128:131], v31, s[20:21]
	global_load_dwordx4 v[132:135], v32, s[20:21]
	global_load_dwordx4 v[136:139], v33, s[20:21]
	global_load_dwordx4 v[140:143], v34, s[20:21]
	global_load_dwordx4 v[144:147], v35, s[20:21]
	v_add_u32_dpp v221, v52, v52 row_ror:8 row_mask:0xf bank_mask:0x3
	v_add_u32_dpp v221, v60, v60 row_ror:8 row_mask:0xf bank_mask:0xc
	v_add_u32_dpp v222, v53, v53 row_ror:8 row_mask:0xf bank_mask:0x3
	v_add_u32_dpp v222, v61, v61 row_ror:8 row_mask:0xf bank_mask:0xc
	v_add_u32_dpp v223, v54, v54 row_ror:8 row_mask:0xf bank_mask:0x3
	v_add_u32_dpp v223, v62, v62 row_ror:8 row_mask:0xf bank_mask:0xc
	v_add_u32_dpp v224, v55, v55 row_ror:8 row_mask:0xf bank_mask:0x3
	v_add_u32_dpp v224, v63, v63 row_ror:8 row_mask:0xf bank_mask:0xc
	v_add_u32_dpp v225, v56, v56 row_ror:8 row_mask:0xf bank_mask:0x3
	v_add_u32_dpp v225, v64, v64 row_ror:8 row_mask:0xf bank_mask:0xc
	v_add_u32_dpp v226, v57, v57 row_ror:8 row_mask:0xf bank_mask:0x3
	v_add_u32_dpp v226, v65, v65 row_ror:8 row_mask:0xf bank_mask:0xc
	v_add_u32_dpp v227, v58, v58 row_ror:8 row_mask:0xf bank_mask:0x3
	v_add_u32_dpp v227, v66, v66 row_ror:8 row_mask:0xf bank_mask:0xc
	v_add_u32_dpp v228, v59, v59 row_ror:8 row_mask:0xf bank_mask:0x3
	v_add_u32_dpp v228, v67, v67 row_ror:8 row_mask:0xf bank_mask:0xc
	v_add_u32_dpp v229, v221, v221 row_half_mirror row_mask:0xf bank_mask:0x5
	v_add_u32_dpp v229, v225, v225 row_half_mirror row_mask:0xf bank_mask:0xa
	v_add_u32_dpp v230, v222, v222 row_half_mirror row_mask:0xf bank_mask:0x5
	v_add_u32_dpp v230, v226, v226 row_half_mirror row_mask:0xf bank_mask:0xa
	v_add_u32_dpp v231, v223, v223 row_half_mirror row_mask:0xf bank_mask:0x5
	v_add_u32_dpp v231, v227, v227 row_half_mirror row_mask:0xf bank_mask:0xa
	v_add_u32_dpp v232, v224, v224 row_half_mirror row_mask:0xf bank_mask:0x5
	v_add_u32_dpp v232, v228, v228 row_half_mirror row_mask:0xf bank_mask:0xa
	v_add_u32_dpp v233, v229, v229 quad_perm:[2,3,0,1] row_mask:0xf bank_mask:0xf
	v_add_u32_dpp v234, v230, v230 quad_perm:[2,3,0,1] row_mask:0xf bank_mask:0xf
	v_add_u32_dpp v235, v231, v231 quad_perm:[2,3,0,1] row_mask:0xf bank_mask:0xf
	s_nop 0
	v_add_u32_dpp v236, v232, v232 quad_perm:[2,3,0,1] row_mask:0xf bank_mask:0xf
	v_cndmask_b32_e64 v237, v235, v233, s[2:3]
	v_cndmask_b32_e64 v238, v236, v234, s[2:3]
	v_add_u32_e32 v214, s46, v4
	s_nop 1
	v_add_u32_dpp v239, v237, v237 quad_perm:[1,0,3,2] row_mask:0xf bank_mask:0xf
	v_add_u32_dpp v240, v238, v238 quad_perm:[1,0,3,2] row_mask:0xf bank_mask:0xf
	v_cndmask_b32_e64 v241, v240, v239, s[4:5]
	global_store_dword v214, v241, s[14:15]
	s_waitcnt vmcnt(36)
	v_dot4c_i32_i8_e32 v68, v148, v16
	s_waitcnt vmcnt(35)
	v_dot4c_i32_i8_e32 v69, v152, v16
	s_waitcnt vmcnt(34)
	v_dot4c_i32_i8_e32 v70, v156, v16
	s_waitcnt vmcnt(33)
	v_dot4c_i32_i8_e32 v71, v160, v16
	s_waitcnt vmcnt(32)
	v_dot4c_i32_i8_e32 v72, v164, v16
	s_waitcnt vmcnt(31)
	v_dot4c_i32_i8_e32 v73, v168, v16
	s_waitcnt vmcnt(30)
	v_dot4c_i32_i8_e32 v74, v172, v16
	s_waitcnt vmcnt(29)
	v_dot4c_i32_i8_e32 v75, v176, v16
	s_waitcnt vmcnt(28)
	v_dot4c_i32_i8_e32 v76, v180, v16
	s_waitcnt vmcnt(27)
	v_dot4c_i32_i8_e32 v77, v184, v16
	s_waitcnt vmcnt(26)
	v_dot4c_i32_i8_e32 v78, v190, v16
	s_waitcnt vmcnt(25)
	v_dot4c_i32_i8_e32 v79, v194, v16
	s_waitcnt vmcnt(24)
	v_dot4c_i32_i8_e32 v80, v198, v16
	s_waitcnt vmcnt(23)
	v_dot4c_i32_i8_e32 v81, v202, v16
	s_waitcnt vmcnt(22)
	v_dot4c_i32_i8_e32 v82, v206, v16
	s_waitcnt vmcnt(21)
; DI void phase9(const Params& p, char* smem, int rep) {
;     ...
;         for (int q = 0; q < 4; ++q) { const int4 v = *(const int4*)(lw + g * 32 + batch * 16 + q * 4); ida[q * 4] = v.x; ida[q * 4 + 1] = v.y; ida[q * 4 + 2] = v.z; ida[q * 4 + 3] = v.w; }
;         u32x4 rows[16];
; #pragma unroll
;         for (int k = 0; k < 16; ++k) rows[k] = *(const u32x4*)(ub + (size_t)ida[k] * 2048);
;         int part[16];
; #pragma unroll
;         for (int k = 0; k < 16; ++k) {
;           int acc = 0;
; #pragma unroll
;           for (int d = 0; d < 4; ++d) acc = __builtin_amdgcn_sdot4((int)rows[k][d], (int)hq[d], acc, false);
;           part[k] = acc;
;         }
;         int q8[8], q4[4], q2[2];
; #pragma unroll
;         for (int k = 0; k < 8; ++k) q8[k] = (b3 ? part[8 + k] : part[k]) + __shfl_xor(b3 ? part[k] : part[8 + k], 8);
; #pragma unroll
;         for (int k = 0; k < 4; ++k) q4[k] = (b2 ? q8[4 + k] : q8[k]) + __shfl_xor(b2 ? q8[k] : q8[4 + k], 4);
; #pragma unroll
;         for (int k = 0; k < 2; ++k) q2[k] = (b1 ? q4[2 + k] : q4[k]) + __shfl_xor(b1 ? q4[k] : q4[2 + k], 2);
;         const int rr = (b0 ? q2[1] : q2[0]) + __shfl_xor(b0 ? q2[0] : q2[1], 1);
;         PA[((size_t)s * T_ + tok) * 128 + 4 * (batch * 16 + l15) + g] = rr;
;       }
	v_dot4c_i32_i8_e32 v83, v210, v16
	v_dot4c_i32_i8_e32 v68, v149, v17
	v_dot4c_i32_i8_e32 v69, v153, v17
	v_dot4c_i32_i8_e32 v70, v157, v17
	v_dot4c_i32_i8_e32 v71, v161, v17
	v_dot4c_i32_i8_e32 v72, v165, v17
	v_dot4c_i32_i8_e32 v73, v169, v17
	v_dot4c_i32_i8_e32 v74, v173, v17
	v_dot4c_i32_i8_e32 v75, v177, v17
	v_dot4c_i32_i8_e32 v76, v181, v17
	v_dot4c_i32_i8_e32 v77, v185, v17
	v_dot4c_i32_i8_e32 v78, v191, v17
	v_dot4c_i32_i8_e32 v79, v195, v17
	v_dot4c_i32_i8_e32 v80, v199, v17
	v_dot4c_i32_i8_e32 v81, v203, v17
	v_dot4c_i32_i8_e32 v82, v207, v17
	v_dot4c_i32_i8_e32 v83, v211, v17
	v_dot4c_i32_i8_e32 v68, v150, v18
	v_dot4c_i32_i8_e32 v69, v154, v18
	v_dot4c_i32_i8_e32 v70, v158, v18
	v_dot4c_i32_i8_e32 v71, v162, v18
	v_dot4c_i32_i8_e32 v72, v166, v18
	v_dot4c_i32_i8_e32 v73, v170, v18
	v_dot4c_i32_i8_e32 v74, v174, v18
	v_dot4c_i32_i8_e32 v75, v178, v18
	v_dot4c_i32_i8_e32 v76, v182, v18
	v_dot4c_i32_i8_e32 v77, v186, v18
	v_dot4c_i32_i8_e32 v78, v192, v18
	v_dot4c_i32_i8_e32 v79, v196, v18
	v_dot4c_i32_i8_e32 v80, v200, v18
	v_dot4c_i32_i8_e32 v81, v204, v18
	v_dot4c_i32_i8_e32 v82, v208, v18
	v_dot4c_i32_i8_e32 v83, v212, v18
	v_dot4c_i32_i8_e32 v68, v151, v19
	v_dot4c_i32_i8_e32 v69, v155, v19
	v_dot4c_i32_i8_e32 v70, v159, v19
	v_dot4c_i32_i8_e32 v71, v163, v19
	v_dot4c_i32_i8_e32 v72, v167, v19
	v_dot4c_i32_i8_e32 v73, v171, v19
	v_dot4c_i32_i8_e32 v74, v175, v19
	v_dot4c_i32_i8_e32 v75, v179, v19
	v_dot4c_i32_i8_e32 v76, v183, v19
	v_dot4c_i32_i8_e32 v77, v187, v19
	v_dot4c_i32_i8_e32 v78, v193, v19
	v_dot4c_i32_i8_e32 v79, v197, v19
	v_dot4c_i32_i8_e32 v80, v201, v19
	v_dot4c_i32_i8_e32 v81, v205, v19
	v_dot4c_i32_i8_e32 v82, v209, v19
	v_dot4c_i32_i8_e32 v83, v213, v19
	v_lshl_add_u32 v36, v36, 11, v2
	v_lshl_add_u32 v37, v37, 11, v2
	v_lshl_add_u32 v38, v38, 11, v2
	v_lshl_add_u32 v39, v39, 11, v2
	v_lshl_add_u32 v40, v40, 11, v2
	v_lshl_add_u32 v41, v41, 11, v2
	v_lshl_add_u32 v42, v42, 11, v2
	v_lshl_add_u32 v43, v43, 11, v2
	v_lshl_add_u32 v44, v44, 11, v2
	v_lshl_add_u32 v45, v45, 11, v2
	v_lshl_add_u32 v46, v46, 11, v2
	v_lshl_add_u32 v47, v47, 11, v2
	v_lshl_add_u32 v48, v48, 11, v2
	v_lshl_add_u32 v49, v49, 11, v2
	v_lshl_add_u32 v50, v50, 11, v2
	v_lshl_add_u32 v51, v51, 11, v2
	global_load_dwordx4 v[148:151], v36, s[20:21]
	global_load_dwordx4 v[152:155], v37, s[20:21]
	global_load_dwordx4 v[156:159], v38, s[20:21]
	global_load_dwordx4 v[160:163], v39, s[20:21]
	global_load_dwordx4 v[164:167], v40, s[20:21]
	global_load_dwordx4 v[168:171], v41, s[20:21]
	global_load_dwordx4 v[172:175], v42, s[20:21]
	global_load_dwordx4 v[176:179], v43, s[20:21]
	global_load_dwordx4 v[180:183], v44, s[20:21]
	global_load_dwordx4 v[184:187], v45, s[20:21]
	global_load_dwordx4 v[190:193], v46, s[20:21]
	global_load_dwordx4 v[194:197], v47, s[20:21]
	global_load_dwordx4 v[198:201], v48, s[20:21]
	global_load_dwordx4 v[202:205], v49, s[20:21]
	global_load_dwordx4 v[206:209], v50, s[20:21]
	global_load_dwordx4 v[210:213], v51, s[20:21]
	v_add_u32_dpp v221, v68, v68 row_ror:8 row_mask:0xf bank_mask:0x3
	v_add_u32_dpp v221, v76, v76 row_ror:8 row_mask:0xf bank_mask:0xc
	v_add_u32_dpp v222, v69, v69 row_ror:8 row_mask:0xf bank_mask:0x3
	v_add_u32_dpp v222, v77, v77 row_ror:8 row_mask:0xf bank_mask:0xc
	v_add_u32_dpp v223, v70, v70 row_ror:8 row_mask:0xf bank_mask:0x3
	v_add_u32_dpp v223, v78, v78 row_ror:8 row_mask:0xf bank_mask:0xc
	v_add_u32_dpp v224, v71, v71 row_ror:8 row_mask:0xf bank_mask:0x3
	v_add_u32_dpp v224, v79, v79 row_ror:8 row_mask:0xf bank_mask:0xc
	v_add_u32_dpp v225, v72, v72 row_ror:8 row_mask:0xf bank_mask:0x3
	v_add_u32_dpp v225, v80, v80 row_ror:8 row_mask:0xf bank_mask:0xc
	v_add_u32_dpp v226, v73, v73 row_ror:8 row_mask:0xf bank_mask:0x3
	v_add_u32_dpp v226, v81, v81 row_ror:8 row_mask:0xf bank_mask:0xc
	v_add_u32_dpp v227, v74, v74 row_ror:8 row_mask:0xf bank_mask:0x3
	v_add_u32_dpp v227, v82, v82 row_ror:8 row_mask:0xf bank_mask:0xc
	v_add_u32_dpp v228, v75, v75 row_ror:8 row_mask:0xf bank_mask:0x3
	v_add_u32_dpp v228, v83, v83 row_ror:8 row_mask:0xf bank_mask:0xc
	v_add_u32_dpp v229, v221, v221 row_half_mirror row_mask:0xf bank_mask:0x5
	v_add_u32_dpp v229, v225, v225 row_half_mirror row_mask:0xf bank_mask:0xa
	v_add_u32_dpp v230, v222, v222 row_half_mirror row_mask:0xf bank_mask:0x5
	v_add_u32_dpp v230, v226, v226 row_half_mirror row_mask:0xf bank_mask:0xa
	v_add_u32_dpp v231, v223, v223 row_half_mirror row_mask:0xf bank_mask:0x5
	v_add_u32_dpp v231, v227, v227 row_half_mirror row_mask:0xf bank_mask:0xa
	v_add_u32_dpp v232, v224, v224 row_half_mirror row_mask:0xf bank_mask:0x5
	v_add_u32_dpp v232, v228, v228 row_half_mirror row_mask:0xf bank_mask:0xa
	v_add_u32_dpp v233, v229, v229 quad_perm:[2,3,0,1] row_mask:0xf bank_mask:0xf
	v_add_u32_dpp v234, v230, v230 quad_perm:[2,3,0,1] row_mask:0xf bank_mask:0xf
	v_add_u32_dpp v235, v231, v231 quad_perm:[2,3,0,1] row_mask:0xf bank_mask:0xf
	s_nop 0
	v_add_u32_dpp v236, v232, v232 quad_perm:[2,3,0,1] row_mask:0xf bank_mask:0xf
	v_cndmask_b32_e64 v237, v235, v233, s[2:3]
	v_cndmask_b32_e64 v238, v236, v234, s[2:3]
	s_nop 0
	s_nop 1
	v_add_u32_dpp v239, v237, v237 quad_perm:[1,0,3,2] row_mask:0xf bank_mask:0xf
	v_add_u32_dpp v240, v238, v238 quad_perm:[1,0,3,2] row_mask:0xf bank_mask:0xf
	v_cndmask_b32_e64 v241, v240, v239, s[4:5]
	global_store_dword v214, v241, s[14:15] offset:256
	s_add_i32 s48, s48, 1
	s_add_i32 s34, s34, 4
	s_cmp_lt_u32 s48, s49
	s_cbranch_scc0 .Lp9_chunk_done
	s_cmp_lt_u32 s34, 8192
	s_cbranch_scc1 .Lp9_body
	s_branch .Lp9_slice_next
